# plus: tanh-gelu in the S5 output stage via exp2/rcp (5 VALU ops) instead of the two-path tanhf expansion
# speedup vs baseline: 1.0297x; 1.0025x over previous
; #define LAS __attribute__((address_space(3)))
; __device__ __forceinline__ pg8::u32x4 pack8(const f32x4 a, const f32x4 b) { pg8::u32x4 w; w.x = pg8::cvt_pk_bf16(a[0], a[1]); w.y = pg8::cvt_pk_bf16(a[2], a[3]); w.z = pg8::cvt_pk_bf16(b[0], b[1]); w.w = pg8::cvt_pk_bf16(b[2], b[3]); return w; }
; __device__ __forceinline__ void ph_s5_out(unsigned char* lds_, const bf16_t* Z, const bf16_t* TZB, const bf16_t* CQ, const float2* LP, const float* SLOC, const float* lamT, bf16_t* YG, int nrct, int u0, int ustep) { PH_IDS;
;     ...
;                 const bf16x8 cqr = *(const LAS bf16x8*)(sm + O_SL + 9216 + (c16 * 256 + 32 * (4 * d + ph) + 8 * kq) * 2), cqi = *(const LAS bf16x8*)(sm + O_SL + 9216 + (c16 * 256 + 32 * (4 * d + 2 + ph) + 8 * kq) * 2);
;                 const bf16x8 xre = *(const LAS bf16x8*)(xb + (4 * d + ph) * 64), xim = *(const LAS bf16x8*)(xb + (4 * d + 2 + ph) * 64);
;                 float yr[8], yi[8], lr[8], li[8];
; #pragma unroll
;                 for (int j = 0; j < 8; ++j) {
;                     const int p_ = 32 * ph + 8 * kq + j;
;                     const f32x2v l1 = *(const LAS f32x2v*)(sm + O_SL + (d * 64 + p_) * 8), ls = *(const LAS f32x2v*)(sm + O_SL + (128 + (wid * 2 + d) * 64 + p_) * 8);
;                     const float xr = __uint_as_float((unsigned)(unsigned short)xre[j] << 16), xi = __uint_as_float((unsigned)(unsigned short)xim[j] << 16);
;                     yr[j] = ls.x * xr - ls.y * xi; yi[j] = ls.x * xi + ls.y * xr; lr[j] = l1.x; li[j] = l1.y;
;                 }
; #pragma unroll
;                 for (int s8 = 0; s8 < 8; ++s8) {
;                     const int i = d == 0 ? s8 : 7 - s8;
;                     const bf16x8 bre = __builtin_bit_cast(bf16x8, pack8((f32x4){yr[0], yr[1], yr[2], yr[3]}, (f32x4){yr[4], yr[5], yr[6], yr[7]}));
;                     const bf16x8 bim = __builtin_bit_cast(bf16x8, pack8((f32x4){yi[0], yi[1], yi[2], yi[3]}, (f32x4){yi[4], yi[5], yi[6], yi[7]}));
.LBB0_882:
	s_lshl_b32 s8, s9, 6
	v_lshl_or_b32 v34, s9, 5, v58
	v_add_u32_e32 v35, s8, v60
	v_add_u32_e32 v42, s8, v59
	v_or_b32_e32 v45, 2, v34
	v_or_b32_e32 v46, 4, v34
	v_or_b32_e32 v47, 6, v34
	v_lshl_add_u32 v43, v34, 3, s88
	v_or_b32_e32 v44, s5, v34
	ds_read_b128 v[38:41], v35 offset:256
	ds_read_b128 v[34:37], v35 offset:384
	ds_read_b128 v[62:65], v42 offset:256
	ds_read_b128 v[66:69], v42 offset:384
	v_lshl_add_u32 v50, v45, 3, s88
	v_or_b32_e32 v42, s5, v45
	v_lshl_add_u32 v45, v46, 3, s88
	v_or_b32_e32 v46, s5, v46
	v_or_b32_e32 v51, s5, v47
	v_lshl_add_u32 v44, v44, 3, s88
	v_lshl_add_u32 v48, v47, 3, s88
	ds_read_b128 v[54:57], v43 offset:512
	ds_read_b128 v[70:73], v44
	v_lshl_add_u32 v78, v46, 3, s88
	v_lshl_add_u32 v82, v51, 3, s88
	v_lshl_add_u32 v61, v42, 3, s88
	ds_read_b128 v[42:45], v45 offset:512
	ds_read_b128 v[46:49], v48 offset:512
	ds_read_b128 v[50:53], v50 offset:512
	ds_read_b128 v[74:77], v61
	ds_read_b128 v[78:81], v78
	ds_read_b128 v[82:85], v82
	s_waitcnt lgkmcnt(8)
	v_lshlrev_b32_e32 v88, 16, v66
	v_and_b32_e32 v66, 0xffff0000, v66
	v_lshlrev_b32_e32 v86, 16, v62
	v_and_b32_e32 v62, 0xffff0000, v62
	v_lshlrev_b32_e32 v92, 16, v67
	v_and_b32_e32 v96, 0xffff0000, v67
	v_lshlrev_b32_e32 v100, 16, v68
	v_and_b32_e32 v68, 0xffff0000, v68
	v_lshlrev_b32_e32 v104, 16, v69
	v_and_b32_e32 v108, 0xffff0000, v69
	s_waitcnt lgkmcnt(6)
	v_pk_mul_f32 v[88:89], v[70:71], v[88:89] op_sel_hi:[1,0]
	v_pk_mul_f32 v[66:67], v[72:73], v[66:67] op_sel_hi:[1,0]
	v_lshlrev_b32_e32 v90, 16, v63
	v_and_b32_e32 v94, 0xffff0000, v63
	v_lshlrev_b32_e32 v98, 16, v64
	v_and_b32_e32 v64, 0xffff0000, v64
	v_lshlrev_b32_e32 v102, 16, v65
	v_and_b32_e32 v106, 0xffff0000, v65
	v_pk_fma_f32 v[110:111], v[70:71], v[86:87], v[88:89] op_sel:[1,0,0] op_sel_hi:[0,0,1]
	v_pk_fma_f32 v[70:71], v[70:71], v[86:87], v[88:89] op_sel:[1,0,0] op_sel_hi:[0,0,1] neg_lo:[0,0,1] neg_hi:[0,0,1]
	v_pk_fma_f32 v[86:87], v[72:73], v[62:63], v[66:67] op_sel:[1,0,0] op_sel_hi:[0,0,1]
	v_pk_fma_f32 v[62:63], v[72:73], v[62:63], v[66:67] op_sel:[1,0,0] op_sel_hi:[0,0,1] neg_lo:[0,0,1] neg_hi:[0,0,1]
	s_waitcnt lgkmcnt(2)
	v_pk_mul_f32 v[66:67], v[74:75], v[92:93] op_sel_hi:[1,0]
	v_pk_mul_f32 v[72:73], v[76:77], v[96:97] op_sel_hi:[1,0]
	s_waitcnt lgkmcnt(1)
	v_pk_mul_f32 v[88:89], v[78:79], v[100:101] op_sel_hi:[1,0]
	v_pk_mul_f32 v[68:69], v[80:81], v[68:69] op_sel_hi:[1,0]
	s_waitcnt lgkmcnt(0)
	v_pk_mul_f32 v[92:93], v[82:83], v[104:105] op_sel_hi:[1,0]
	v_pk_mul_f32 v[96:97], v[84:85], v[108:109] op_sel_hi:[1,0]
	v_mov_b32_e32 v100, v110
	v_mov_b32_e32 v101, v71
	v_pk_mov_b32 v[104:105], v[70:71], v[110:111] op_sel:[1,0]
	v_mul_f32_e32 v70, v55, v110
	v_mul_f32_e32 v108, v55, v71
	v_mov_b32_e32 v112, v86
	v_mov_b32_e32 v113, v63
	v_pk_mov_b32 v[114:115], v[62:63], v[86:87] op_sel:[1,0]
	v_mul_f32_e32 v116, v57, v86
	v_mul_f32_e32 v118, v57, v63
	v_pk_fma_f32 v[120:121], v[74:75], v[90:91], v[66:67] op_sel:[1,0,0] op_sel_hi:[0,0,1]
	v_pk_fma_f32 v[66:67], v[74:75], v[90:91], v[66:67] op_sel:[1,0,0] op_sel_hi:[0,0,1] neg_lo:[0,0,1] neg_hi:[0,0,1]
	v_pk_fma_f32 v[74:75], v[76:77], v[94:95], v[72:73] op_sel:[1,0,0] op_sel_hi:[0,0,1]
	v_pk_fma_f32 v[72:73], v[76:77], v[94:95], v[72:73] op_sel:[1,0,0] op_sel_hi:[0,0,1] neg_lo:[0,0,1] neg_hi:[0,0,1]
	v_pk_fma_f32 v[76:77], v[78:79], v[98:99], v[88:89] op_sel:[1,0,0] op_sel_hi:[0,0,1]
	v_pk_fma_f32 v[78:79], v[78:79], v[98:99], v[88:89] op_sel:[1,0,0] op_sel_hi:[0,0,1] neg_lo:[0,0,1] neg_hi:[0,0,1]
	v_pk_fma_f32 v[88:89], v[80:81], v[64:65], v[68:69] op_sel:[1,0,0] op_sel_hi:[0,0,1]
	v_pk_fma_f32 v[64:65], v[80:81], v[64:65], v[68:69] op_sel:[1,0,0] op_sel_hi:[0,0,1] neg_lo:[0,0,1] neg_hi:[0,0,1]
	v_pk_fma_f32 v[80:81], v[82:83], v[102:103], v[92:93] op_sel:[1,0,0] op_sel_hi:[0,0,1]
	v_pk_fma_f32 v[68:69], v[82:83], v[102:103], v[92:93] op_sel:[1,0,0] op_sel_hi:[0,0,1] neg_lo:[0,0,1] neg_hi:[0,0,1]
	v_pk_fma_f32 v[82:83], v[84:85], v[106:107], v[96:97] op_sel:[1,0,0] op_sel_hi:[0,0,1]
	v_pk_fma_f32 v[84:85], v[84:85], v[106:107], v[96:97] op_sel:[1,0,0] op_sel_hi:[0,0,1] neg_lo:[0,0,1] neg_hi:[0,0,1]
	v_cvt_pk_bf16_f32 v62, v71, v63
	v_pk_fma_f32 v[90:91], v[54:55], v[104:105], v[70:71] op_sel_hi:[1,1,0] neg_lo:[0,0,1] neg_hi:[0,0,1]
	v_pk_fma_f32 v[70:71], v[54:55], v[100:101], v[108:109] op_sel_hi:[1,1,0]
	v_pk_fma_f32 v[92:93], v[56:57], v[114:115], v[116:117] op_sel_hi:[1,1,0] neg_lo:[0,0,1] neg_hi:[0,0,1]
	v_pk_fma_f32 v[94:95], v[56:57], v[112:113], v[118:119] op_sel_hi:[1,1,0]
	v_mov_b32_e32 v96, v120
	v_mov_b32_e32 v97, v67
	v_pk_mov_b32 v[98:99], v[66:67], v[120:121] op_sel:[1,0]
	v_mul_f32_e32 v100, v51, v120
	v_mul_f32_e32 v102, v51, v67
	v_mov_b32_e32 v104, v74
	v_mov_b32_e32 v105, v73
	v_pk_mov_b32 v[106:107], v[72:73], v[74:75] op_sel:[1,0]
	v_cvt_pk_bf16_f32 v63, v67, v73
	v_mul_f32_e32 v72, v53, v74
	v_mul_f32_e32 v108, v53, v73
	v_mov_b32_e32 v112, v76
	v_mov_b32_e32 v113, v79
	v_pk_mov_b32 v[114:115], v[78:79], v[76:77] op_sel:[1,0]
	v_mul_f32_e32 v78, v43, v76
	v_mul_f32_e32 v116, v43, v79
	v_mov_b32_e32 v118, v88
	v_mov_b32_e32 v119, v65
	v_pk_mov_b32 v[122:123], v[64:65], v[88:89] op_sel:[1,0]
	v_cvt_pk_bf16_f32 v64, v79, v65
	v_mul_f32_e32 v126, v45, v65
	v_mov_b32_e32 v128, v80
	v_mov_b32_e32 v129, v69
	v_pk_mov_b32 v[132:133], v[68:69], v[80:81] op_sel:[1,0]
	v_mul_f32_e32 v136, v47, v69
	v_mov_b32_e32 v138, v82
	v_mov_b32_e32 v139, v85
	v_cvt_pk_bf16_f32 v65, v69, v85
	v_cvt_pk_bf16_f32 v66, v110, v86
	v_cvt_pk_bf16_f32 v67, v120, v74
	v_cvt_pk_bf16_f32 v68, v76, v88
	v_mul_f32_e32 v76, v49, v85
	v_mul_f32_e32 v124, v45, v88
	v_mul_f32_e32 v134, v47, v80
	v_pk_mov_b32 v[140:141], v[84:85], v[82:83] op_sel:[1,0]
; __device__ __forceinline__ pg8::u32x4 pack8(const f32x4 a, const f32x4 b) { pg8::u32x4 w; w.x = pg8::cvt_pk_bf16(a[0], a[1]); w.y = pg8::cvt_pk_bf16(a[2], a[3]); w.z = pg8::cvt_pk_bf16(b[0], b[1]); w.w = pg8::cvt_pk_bf16(b[2], b[3]); return w; }
; __device__ __forceinline__ void ph_s5_out(unsigned char* lds_, const bf16_t* Z, const bf16_t* TZB, const bf16_t* CQ, const float2* LP, const float* SLOC, const float* lamT, bf16_t* YG, int nrct, int u0, int ustep) { PH_IDS;
;     ...
;                 for (int s8 = 0; s8 < 8; ++s8) {
;                     const int i = d == 0 ? s8 : 7 - s8;
;                     const bf16x8 bre = __builtin_bit_cast(bf16x8, pack8((f32x4){yr[0], yr[1], yr[2], yr[3]}, (f32x4){yr[4], yr[5], yr[6], yr[7]}));
;                     const bf16x8 bim = __builtin_bit_cast(bf16x8, pack8((f32x4){yi[0], yi[1], yi[2], yi[3]}, (f32x4){yi[4], yi[5], yi[6], yi[7]}));
;                     acc8[i] = __builtin_amdgcn_mfma_f32_16x16x32_bf16(cqr, bre, acc8[i], 0, 0, 0);
;                     acc8[i] = __builtin_amdgcn_mfma_f32_16x16x32_bf16(cqi, bim, acc8[i], 0, 0, 0);
;                     if (s8 < 7) {
; #pragma unroll
;                         for (int j = 0; j < 8; ++j) { const float a = yr[j], c = yi[j]; yr[j] = lr[j] * a - li[j] * c; yi[j] = lr[j] * c + li[j] * a; }
;                     }
	v_cvt_pk_bf16_f32 v69, v80, v82
	v_mul_f32_e32 v74, v49, v82
	v_pk_fma_f32 v[80:81], v[50:51], v[98:99], v[100:101] op_sel_hi:[1,1,0] neg_lo:[0,0,1] neg_hi:[0,0,1]
	v_pk_fma_f32 v[82:83], v[50:51], v[96:97], v[102:103] op_sel_hi:[1,1,0]
	v_pk_fma_f32 v[84:85], v[52:53], v[106:107], v[72:73] op_sel_hi:[1,1,0] neg_lo:[0,0,1] neg_hi:[0,0,1]
	v_pk_fma_f32 v[86:87], v[52:53], v[104:105], v[108:109] op_sel_hi:[1,1,0]
	v_pk_fma_f32 v[88:89], v[42:43], v[112:113], v[116:117] op_sel_hi:[1,1,0]
	v_pk_fma_f32 v[98:99], v[44:45], v[118:119], v[126:127] op_sel_hi:[1,1,0]
	v_pk_fma_f32 v[102:103], v[46:47], v[128:129], v[136:137] op_sel_hi:[1,1,0]
	v_pk_fma_f32 v[76:77], v[48:49], v[138:139], v[76:77] op_sel_hi:[1,1,0]
	v_pk_mul_f32 v[104:105], v[54:55], v[70:71] op_sel_hi:[1,0]
	v_pk_mul_f32 v[106:107], v[56:57], v[94:95] op_sel_hi:[1,0]
	v_pk_fma_f32 v[78:79], v[42:43], v[114:115], v[78:79] op_sel_hi:[1,1,0] neg_lo:[0,0,1] neg_hi:[0,0,1]
	v_pk_fma_f32 v[96:97], v[44:45], v[122:123], v[124:125] op_sel_hi:[1,1,0] neg_lo:[0,0,1] neg_hi:[0,0,1]
	v_pk_fma_f32 v[100:101], v[46:47], v[132:133], v[134:135] op_sel_hi:[1,1,0] neg_lo:[0,0,1] neg_hi:[0,0,1]
	v_mfma_f32_16x16x32_bf16 v[10:13], v[38:41], v[62:65], v[10:13]
	v_pk_fma_f32 v[74:75], v[48:49], v[140:141], v[74:75] op_sel_hi:[1,1,0] neg_lo:[0,0,1] neg_hi:[0,0,1]
	v_cvt_pk_bf16_f32 v62, v90, v92
	v_cvt_pk_bf16_f32 v63, v80, v84
	v_cvt_pk_bf16_f32 v64, v78, v96
	v_mfma_f32_16x16x32_bf16 v[10:13], v[34:37], v[66:69], v[10:13]
	v_cvt_pk_bf16_f32 v65, v100, v74
	v_cvt_pk_bf16_f32 v70, v70, v94
	v_cvt_pk_bf16_f32 v71, v82, v86
	v_cvt_pk_bf16_f32 v72, v88, v98
	v_cvt_pk_bf16_f32 v73, v102, v76
	v_fma_f32 v94, v55, v90, v104
	v_fma_f32 v95, v54, v90, v105
	v_pk_fma_f32 v[90:91], v[54:55], v[90:91], v[104:105] op_sel:[1,0,0] op_sel_hi:[0,0,1] neg_lo:[0,0,1] neg_hi:[0,0,1]
	v_pk_fma_f32 v[104:105], v[56:57], v[92:93], v[106:107] op_sel:[1,0,0] op_sel_hi:[0,0,1]
	v_pk_fma_f32 v[92:93], v[56:57], v[92:93], v[106:107] op_sel:[1,0,0] op_sel_hi:[0,0,1] neg_lo:[0,0,1] neg_hi:[0,0,1]
	v_pk_mul_f32 v[82:83], v[50:51], v[82:83] op_sel_hi:[1,0]
	v_pk_mul_f32 v[86:87], v[52:53], v[86:87] op_sel_hi:[1,0]
	v_pk_mul_f32 v[88:89], v[42:43], v[88:89] op_sel_hi:[1,0]
	v_pk_mul_f32 v[98:99], v[44:45], v[98:99] op_sel_hi:[1,0]
	v_pk_mul_f32 v[102:103], v[46:47], v[102:103] op_sel_hi:[1,0]
	v_pk_mul_f32 v[76:77], v[48:49], v[76:77] op_sel_hi:[1,0]
	v_mfma_f32_16x16x32_bf16 v[2:5], v[38:41], v[62:65], v[2:5]
	v_mov_b32_e32 v64, v94
	v_mov_b32_e32 v65, v91
	v_pk_mov_b32 v[106:107], v[90:91], v[94:95] op_sel:[1,0]
	v_mul_f32_e32 v90, v55, v94
	v_mul_f32_e32 v108, v55, v91
	v_mov_b32_e32 v110, v104
	v_mov_b32_e32 v111, v93
	v_pk_mov_b32 v[112:113], v[92:93], v[104:105] op_sel:[1,0]
	v_mul_f32_e32 v92, v57, v104
	v_mul_f32_e32 v114, v57, v93
	v_pk_fma_f32 v[116:117], v[50:51], v[80:81], v[82:83] op_sel:[1,0,0] op_sel_hi:[0,0,1]
	v_pk_fma_f32 v[80:81], v[50:51], v[80:81], v[82:83] op_sel:[1,0,0] op_sel_hi:[0,0,1] neg_lo:[0,0,1] neg_hi:[0,0,1]
	v_pk_fma_f32 v[82:83], v[52:53], v[84:85], v[86:87] op_sel:[1,0,0] op_sel_hi:[0,0,1]
	v_pk_fma_f32 v[84:85], v[52:53], v[84:85], v[86:87] op_sel:[1,0,0] op_sel_hi:[0,0,1] neg_lo:[0,0,1] neg_hi:[0,0,1]
	v_pk_fma_f32 v[86:87], v[42:43], v[78:79], v[88:89] op_sel:[1,0,0] op_sel_hi:[0,0,1]
	v_pk_fma_f32 v[78:79], v[42:43], v[78:79], v[88:89] op_sel:[1,0,0] op_sel_hi:[0,0,1] neg_lo:[0,0,1] neg_hi:[0,0,1]
	v_pk_fma_f32 v[88:89], v[44:45], v[96:97], v[98:99] op_sel:[1,0,0] op_sel_hi:[0,0,1]
	v_pk_fma_f32 v[96:97], v[44:45], v[96:97], v[98:99] op_sel:[1,0,0] op_sel_hi:[0,0,1] neg_lo:[0,0,1] neg_hi:[0,0,1]
	v_pk_fma_f32 v[98:99], v[46:47], v[100:101], v[102:103] op_sel:[1,0,0] op_sel_hi:[0,0,1]
	v_pk_fma_f32 v[100:101], v[46:47], v[100:101], v[102:103] op_sel:[1,0,0] op_sel_hi:[0,0,1] neg_lo:[0,0,1] neg_hi:[0,0,1]
	v_pk_fma_f32 v[102:103], v[48:49], v[74:75], v[76:77] op_sel:[1,0,0] op_sel_hi:[0,0,1]
	v_pk_fma_f32 v[118:119], v[48:49], v[74:75], v[76:77] op_sel:[1,0,0] op_sel_hi:[0,0,1] neg_lo:[0,0,1] neg_hi:[0,0,1]
	v_cvt_pk_bf16_f32 v62, v91, v93
	v_pk_fma_f32 v[90:91], v[54:55], v[106:107], v[90:91] op_sel_hi:[1,1,0] neg_lo:[0,0,1] neg_hi:[0,0,1]
	v_pk_fma_f32 v[106:107], v[54:55], v[64:65], v[108:109] op_sel_hi:[1,1,0]
	v_pk_fma_f32 v[92:93], v[56:57], v[112:113], v[92:93] op_sel_hi:[1,1,0] neg_lo:[0,0,1] neg_hi:[0,0,1]
	v_pk_fma_f32 v[108:109], v[56:57], v[110:111], v[114:115] op_sel_hi:[1,1,0]
	v_mov_b32_e32 v110, v116
	v_mov_b32_e32 v111, v81
	v_pk_mov_b32 v[112:113], v[80:81], v[116:117] op_sel:[1,0]
	v_mul_f32_e32 v80, v51, v116
	v_mul_f32_e32 v114, v51, v81
	v_mov_b32_e32 v120, v82
	v_mov_b32_e32 v121, v85
	v_cvt_pk_bf16_f32 v63, v81, v85
	v_mul_f32_e32 v124, v53, v85
	v_mov_b32_e32 v126, v86
	v_mov_b32_e32 v127, v79
	v_pk_mov_b32 v[128:129], v[78:79], v[86:87] op_sel:[1,0]
	v_mul_f32_e32 v78, v43, v86
	v_mul_f32_e32 v132, v43, v79
	v_mov_b32_e32 v134, v88
	v_mov_b32_e32 v135, v97
	v_cvt_pk_bf16_f32 v64, v79, v97
	v_mul_f32_e32 v138, v45, v97
	v_mov_b32_e32 v140, v98
	v_mov_b32_e32 v141, v101
	v_mul_f32_e32 v144, v47, v101
	v_mov_b32_e32 v146, v102
	v_mov_b32_e32 v147, v119
	v_cvt_pk_bf16_f32 v65, v101, v119
	v_cvt_pk_bf16_f32 v74, v94, v104
	v_cvt_pk_bf16_f32 v75, v116, v82
	v_cvt_pk_bf16_f32 v76, v86, v88
	v_mul_f32_e32 v86, v49, v119
	v_pk_mov_b32 v[122:123], v[84:85], v[82:83] op_sel:[1,0]
	v_mul_f32_e32 v84, v53, v82
	v_pk_mov_b32 v[136:137], v[96:97], v[88:89] op_sel:[1,0]
	v_mul_f32_e32 v96, v45, v88
	v_pk_mov_b32 v[142:143], v[100:101], v[98:99] op_sel:[1,0]
	v_mul_f32_e32 v100, v47, v98
	v_pk_mov_b32 v[148:149], v[118:119], v[102:103] op_sel:[1,0]
	v_cvt_pk_bf16_f32 v77, v98, v102
; __device__ __forceinline__ pg8::u32x4 pack8(const f32x4 a, const f32x4 b) { pg8::u32x4 w; w.x = pg8::cvt_pk_bf16(a[0], a[1]); w.y = pg8::cvt_pk_bf16(a[2], a[3]); w.z = pg8::cvt_pk_bf16(b[0], b[1]); w.w = pg8::cvt_pk_bf16(b[2], b[3]); return w; }
; __device__ __forceinline__ void ph_s5_out(unsigned char* lds_, const bf16_t* Z, const bf16_t* TZB, const bf16_t* CQ, const float2* LP, const float* SLOC, const float* lamT, bf16_t* YG, int nrct, int u0, int ustep) { PH_IDS;
;     ...
;                 for (int s8 = 0; s8 < 8; ++s8) {
;                     const int i = d == 0 ? s8 : 7 - s8;
;                     const bf16x8 bre = __builtin_bit_cast(bf16x8, pack8((f32x4){yr[0], yr[1], yr[2], yr[3]}, (f32x4){yr[4], yr[5], yr[6], yr[7]}));
;                     const bf16x8 bim = __builtin_bit_cast(bf16x8, pack8((f32x4){yi[0], yi[1], yi[2], yi[3]}, (f32x4){yi[4], yi[5], yi[6], yi[7]}));
;                     acc8[i] = __builtin_amdgcn_mfma_f32_16x16x32_bf16(cqr, bre, acc8[i], 0, 0, 0);
;                     acc8[i] = __builtin_amdgcn_mfma_f32_16x16x32_bf16(cqi, bim, acc8[i], 0, 0, 0);
;                     if (s8 < 7) {
; #pragma unroll
;                         for (int j = 0; j < 8; ++j) { const float a = yr[j], c = yi[j]; yr[j] = lr[j] * a - li[j] * c; yi[j] = lr[j] * c + li[j] * a; }
;                     }
	v_mul_f32_e32 v82, v49, v102
	v_pk_fma_f32 v[80:81], v[50:51], v[112:113], v[80:81] op_sel_hi:[1,1,0] neg_lo:[0,0,1] neg_hi:[0,0,1]
	v_pk_fma_f32 v[88:89], v[50:51], v[110:111], v[114:115] op_sel_hi:[1,1,0]
	v_pk_fma_f32 v[94:95], v[52:53], v[120:121], v[124:125] op_sel_hi:[1,1,0]
	v_pk_fma_f32 v[98:99], v[42:43], v[126:127], v[132:133] op_sel_hi:[1,1,0]
	v_pk_fma_f32 v[102:103], v[44:45], v[134:135], v[138:139] op_sel_hi:[1,1,0]
	v_pk_fma_f32 v[104:105], v[46:47], v[140:141], v[144:145] op_sel_hi:[1,1,0]
	v_pk_fma_f32 v[86:87], v[48:49], v[146:147], v[86:87] op_sel_hi:[1,1,0]
	v_pk_mul_f32 v[110:111], v[54:55], v[106:107] op_sel_hi:[1,0]
	v_pk_mul_f32 v[112:113], v[56:57], v[108:109] op_sel_hi:[1,0]
	v_pk_fma_f32 v[84:85], v[52:53], v[122:123], v[84:85] op_sel_hi:[1,1,0] neg_lo:[0,0,1] neg_hi:[0,0,1]
	v_pk_fma_f32 v[78:79], v[42:43], v[128:129], v[78:79] op_sel_hi:[1,1,0] neg_lo:[0,0,1] neg_hi:[0,0,1]
	v_pk_fma_f32 v[96:97], v[44:45], v[136:137], v[96:97] op_sel_hi:[1,1,0] neg_lo:[0,0,1] neg_hi:[0,0,1]
	v_pk_fma_f32 v[100:101], v[46:47], v[142:143], v[100:101] op_sel_hi:[1,1,0] neg_lo:[0,0,1] neg_hi:[0,0,1]
	v_mfma_f32_16x16x32_bf16 v[18:21], v[38:41], v[62:65], v[18:21]
	v_pk_fma_f32 v[82:83], v[48:49], v[148:149], v[82:83] op_sel_hi:[1,1,0] neg_lo:[0,0,1] neg_hi:[0,0,1]
	v_cvt_pk_bf16_f32 v62, v90, v92
	v_cvt_pk_bf16_f32 v63, v80, v84
	v_cvt_pk_bf16_f32 v64, v78, v96
	v_mfma_f32_16x16x32_bf16 v[2:5], v[34:37], v[70:73], v[2:5]
	v_cvt_pk_bf16_f32 v65, v100, v82
	v_cvt_pk_bf16_f32 v66, v106, v108
	v_cvt_pk_bf16_f32 v67, v88, v94
	v_cvt_pk_bf16_f32 v68, v98, v102
	v_cvt_pk_bf16_f32 v69, v104, v86
	v_fma_f32 v106, v55, v90, v110
	v_fma_f32 v107, v54, v90, v111
	v_pk_fma_f32 v[90:91], v[54:55], v[90:91], v[110:111] op_sel:[1,0,0] op_sel_hi:[0,0,1] neg_lo:[0,0,1] neg_hi:[0,0,1]
	v_pk_fma_f32 v[108:109], v[56:57], v[92:93], v[112:113] op_sel:[1,0,0] op_sel_hi:[0,0,1]
	v_pk_fma_f32 v[92:93], v[56:57], v[92:93], v[112:113] op_sel:[1,0,0] op_sel_hi:[0,0,1] neg_lo:[0,0,1] neg_hi:[0,0,1]
	v_pk_mul_f32 v[88:89], v[50:51], v[88:89] op_sel_hi:[1,0]
	v_pk_mul_f32 v[94:95], v[52:53], v[94:95] op_sel_hi:[1,0]
	v_pk_mul_f32 v[98:99], v[42:43], v[98:99] op_sel_hi:[1,0]
	v_pk_mul_f32 v[70:71], v[44:45], v[102:103] op_sel_hi:[1,0]
	v_pk_mul_f32 v[72:73], v[46:47], v[104:105] op_sel_hi:[1,0]
	v_pk_mul_f32 v[86:87], v[48:49], v[86:87] op_sel_hi:[1,0]
	v_mfma_f32_16x16x32_bf16 v[6:9], v[38:41], v[62:65], v[6:9]
	v_mov_b32_e32 v64, v106
	v_mov_b32_e32 v65, v91
	v_pk_mov_b32 v[102:103], v[90:91], v[106:107] op_sel:[1,0]
	v_mul_f32_e32 v90, v55, v106
	v_mul_f32_e32 v104, v55, v91
	v_mov_b32_e32 v110, v108
	v_mov_b32_e32 v111, v93
	v_pk_mov_b32 v[112:113], v[92:93], v[108:109] op_sel:[1,0]
	v_mul_f32_e32 v92, v57, v108
	v_mul_f32_e32 v114, v57, v93
	v_pk_fma_f32 v[116:117], v[50:51], v[80:81], v[88:89] op_sel:[1,0,0] op_sel_hi:[0,0,1]
	v_pk_fma_f32 v[80:81], v[50:51], v[80:81], v[88:89] op_sel:[1,0,0] op_sel_hi:[0,0,1] neg_lo:[0,0,1] neg_hi:[0,0,1]
	v_pk_fma_f32 v[88:89], v[52:53], v[84:85], v[94:95] op_sel:[1,0,0] op_sel_hi:[0,0,1]
	v_pk_fma_f32 v[84:85], v[52:53], v[84:85], v[94:95] op_sel:[1,0,0] op_sel_hi:[0,0,1] neg_lo:[0,0,1] neg_hi:[0,0,1]
	v_pk_fma_f32 v[94:95], v[42:43], v[78:79], v[98:99] op_sel:[1,0,0] op_sel_hi:[0,0,1]
	v_pk_fma_f32 v[78:79], v[42:43], v[78:79], v[98:99] op_sel:[1,0,0] op_sel_hi:[0,0,1] neg_lo:[0,0,1] neg_hi:[0,0,1]
	v_pk_fma_f32 v[98:99], v[44:45], v[96:97], v[70:71] op_sel:[1,0,0] op_sel_hi:[0,0,1]
	v_pk_fma_f32 v[70:71], v[44:45], v[96:97], v[70:71] op_sel:[1,0,0] op_sel_hi:[0,0,1] neg_lo:[0,0,1] neg_hi:[0,0,1]
	v_pk_fma_f32 v[96:97], v[46:47], v[100:101], v[72:73] op_sel:[1,0,0] op_sel_hi:[0,0,1]
	v_pk_fma_f32 v[72:73], v[46:47], v[100:101], v[72:73] op_sel:[1,0,0] op_sel_hi:[0,0,1] neg_lo:[0,0,1] neg_hi:[0,0,1]
	v_pk_fma_f32 v[100:101], v[48:49], v[82:83], v[86:87] op_sel:[1,0,0] op_sel_hi:[0,0,1]
	v_pk_fma_f32 v[82:83], v[48:49], v[82:83], v[86:87] op_sel:[1,0,0] op_sel_hi:[0,0,1] neg_lo:[0,0,1] neg_hi:[0,0,1]
	v_cvt_pk_bf16_f32 v62, v91, v93
	v_pk_fma_f32 v[86:87], v[54:55], v[102:103], v[90:91] op_sel_hi:[1,1,0] neg_lo:[0,0,1] neg_hi:[0,0,1]
	v_pk_fma_f32 v[90:91], v[54:55], v[64:65], v[104:105] op_sel_hi:[1,1,0]
	v_pk_fma_f32 v[92:93], v[56:57], v[112:113], v[92:93] op_sel_hi:[1,1,0] neg_lo:[0,0,1] neg_hi:[0,0,1]
	v_pk_fma_f32 v[102:103], v[56:57], v[110:111], v[114:115] op_sel_hi:[1,1,0]
	v_mov_b32_e32 v104, v116
	v_mov_b32_e32 v105, v81
	v_pk_mov_b32 v[110:111], v[80:81], v[116:117] op_sel:[1,0]
	v_mul_f32_e32 v80, v51, v116
	v_mul_f32_e32 v112, v51, v81
	v_mov_b32_e32 v114, v88
	v_mov_b32_e32 v115, v85
	v_pk_mov_b32 v[118:119], v[84:85], v[88:89] op_sel:[1,0]
	v_cvt_pk_bf16_f32 v63, v81, v85
	v_mul_f32_e32 v84, v53, v88
	v_mul_f32_e32 v120, v53, v85
	v_mov_b32_e32 v122, v94
	v_mov_b32_e32 v123, v79
	v_mul_f32_e32 v126, v43, v79
	v_mov_b32_e32 v128, v98
	v_mov_b32_e32 v129, v71
	v_pk_mov_b32 v[132:133], v[70:71], v[98:99] op_sel:[1,0]
	v_cvt_pk_bf16_f32 v64, v79, v71
	v_mul_f32_e32 v136, v45, v71
	v_mov_b32_e32 v138, v96
	v_mov_b32_e32 v139, v73
	v_mul_f32_e32 v144, v47, v73
	v_mov_b32_e32 v146, v100
	v_mov_b32_e32 v147, v83
	v_cvt_pk_bf16_f32 v65, v73, v83
	v_cvt_pk_bf16_f32 v70, v106, v108
	v_cvt_pk_bf16_f32 v71, v116, v88
	v_mul_f32_e32 v88, v49, v83
	v_pk_mov_b32 v[124:125], v[78:79], v[94:95] op_sel:[1,0]
	v_mul_f32_e32 v78, v43, v94
	v_mul_f32_e32 v134, v45, v98
	v_pk_mov_b32 v[140:141], v[72:73], v[96:97] op_sel:[1,0]
	v_mul_f32_e32 v142, v47, v96
	v_pk_mov_b32 v[148:149], v[82:83], v[100:101] op_sel:[1,0]
	v_cvt_pk_bf16_f32 v72, v94, v98
	v_cvt_pk_bf16_f32 v73, v96, v100
	v_mul_f32_e32 v82, v49, v100
; __device__ __forceinline__ pg8::u32x4 pack8(const f32x4 a, const f32x4 b) { pg8::u32x4 w; w.x = pg8::cvt_pk_bf16(a[0], a[1]); w.y = pg8::cvt_pk_bf16(a[2], a[3]); w.z = pg8::cvt_pk_bf16(b[0], b[1]); w.w = pg8::cvt_pk_bf16(b[2], b[3]); return w; }
; __device__ __forceinline__ void ph_s5_out(unsigned char* lds_, const bf16_t* Z, const bf16_t* TZB, const bf16_t* CQ, const float2* LP, const float* SLOC, const float* lamT, bf16_t* YG, int nrct, int u0, int ustep) { PH_IDS;
;     ...
;                 for (int s8 = 0; s8 < 8; ++s8) {
;                     const int i = d == 0 ? s8 : 7 - s8;
;                     const bf16x8 bre = __builtin_bit_cast(bf16x8, pack8((f32x4){yr[0], yr[1], yr[2], yr[3]}, (f32x4){yr[4], yr[5], yr[6], yr[7]}));
;                     const bf16x8 bim = __builtin_bit_cast(bf16x8, pack8((f32x4){yi[0], yi[1], yi[2], yi[3]}, (f32x4){yi[4], yi[5], yi[6], yi[7]}));
;                     acc8[i] = __builtin_amdgcn_mfma_f32_16x16x32_bf16(cqr, bre, acc8[i], 0, 0, 0);
;                     acc8[i] = __builtin_amdgcn_mfma_f32_16x16x32_bf16(cqi, bim, acc8[i], 0, 0, 0);
;                     if (s8 < 7) {
; #pragma unroll
;                         for (int j = 0; j < 8; ++j) { const float a = yr[j], c = yi[j]; yr[j] = lr[j] * a - li[j] * c; yi[j] = lr[j] * c + li[j] * a; }
;                     }
;                 }
	v_pk_fma_f32 v[80:81], v[50:51], v[110:111], v[80:81] op_sel_hi:[1,1,0] neg_lo:[0,0,1] neg_hi:[0,0,1]
	v_pk_fma_f32 v[94:95], v[50:51], v[104:105], v[112:113] op_sel_hi:[1,1,0]
	v_pk_fma_f32 v[96:97], v[52:53], v[114:115], v[120:121] op_sel_hi:[1,1,0]
	v_pk_fma_f32 v[98:99], v[42:43], v[122:123], v[126:127] op_sel_hi:[1,1,0]
	v_pk_fma_f32 v[104:105], v[44:45], v[128:129], v[136:137] op_sel_hi:[1,1,0]
	v_pk_fma_f32 v[108:109], v[46:47], v[138:139], v[144:145] op_sel_hi:[1,1,0]
	v_pk_fma_f32 v[88:89], v[48:49], v[146:147], v[88:89] op_sel_hi:[1,1,0]
	v_pk_mul_f32 v[110:111], v[54:55], v[90:91] op_sel_hi:[1,0]
	v_pk_mul_f32 v[112:113], v[56:57], v[102:103] op_sel_hi:[1,0]
	v_mfma_f32_16x16x32_bf16 v[18:21], v[34:37], v[74:77], v[18:21]
	v_pk_fma_f32 v[84:85], v[52:53], v[118:119], v[84:85] op_sel_hi:[1,1,0] neg_lo:[0,0,1] neg_hi:[0,0,1]
	v_pk_fma_f32 v[78:79], v[42:43], v[124:125], v[78:79] op_sel_hi:[1,1,0] neg_lo:[0,0,1] neg_hi:[0,0,1]
	v_pk_fma_f32 v[100:101], v[44:45], v[132:133], v[134:135] op_sel_hi:[1,1,0] neg_lo:[0,0,1] neg_hi:[0,0,1]
	v_pk_fma_f32 v[106:107], v[46:47], v[140:141], v[142:143] op_sel_hi:[1,1,0] neg_lo:[0,0,1] neg_hi:[0,0,1]
	v_mfma_f32_16x16x32_bf16 v[22:25], v[38:41], v[62:65], v[22:25]
	v_pk_fma_f32 v[82:83], v[48:49], v[148:149], v[82:83] op_sel_hi:[1,1,0] neg_lo:[0,0,1] neg_hi:[0,0,1]
	v_cvt_pk_bf16_f32 v62, v86, v92
	v_cvt_pk_bf16_f32 v63, v80, v84
	v_cvt_pk_bf16_f32 v64, v78, v100
	v_mfma_f32_16x16x32_bf16 v[6:9], v[34:37], v[66:69], v[6:9]
	v_cvt_pk_bf16_f32 v65, v106, v82
	v_cvt_pk_bf16_f32 v74, v90, v102
	v_cvt_pk_bf16_f32 v75, v94, v96
	v_cvt_pk_bf16_f32 v76, v98, v104
	v_cvt_pk_bf16_f32 v77, v108, v88
	v_pk_mul_f32 v[88:89], v[48:49], v[88:89] op_sel_hi:[1,0]
	v_pk_fma_f32 v[90:91], v[54:55], v[86:87], v[110:111] op_sel:[1,0,0] op_sel_hi:[0,0,1]
	v_pk_fma_f32 v[86:87], v[54:55], v[86:87], v[110:111] op_sel:[1,0,0] op_sel_hi:[0,0,1] neg_lo:[0,0,1] neg_hi:[0,0,1]
	v_pk_fma_f32 v[102:103], v[56:57], v[92:93], v[112:113] op_sel:[1,0,0] op_sel_hi:[0,0,1]
	v_pk_fma_f32 v[92:93], v[56:57], v[92:93], v[112:113] op_sel:[1,0,0] op_sel_hi:[0,0,1] neg_lo:[0,0,1] neg_hi:[0,0,1]
	v_pk_mul_f32 v[94:95], v[50:51], v[94:95] op_sel_hi:[1,0]
	v_pk_mul_f32 v[96:97], v[52:53], v[96:97] op_sel_hi:[1,0]
	v_pk_mul_f32 v[66:67], v[42:43], v[98:99] op_sel_hi:[1,0]
	v_pk_mul_f32 v[68:69], v[44:45], v[104:105] op_sel_hi:[1,0]
	v_pk_mul_f32 v[98:99], v[46:47], v[108:109] op_sel_hi:[1,0]
	v_mfma_f32_16x16x32_bf16 v[14:17], v[38:41], v[62:65], v[14:17]
	v_fma_f32 v104, v49, v82, v88
	v_fma_f32 v105, v48, v82, v89
	v_pk_fma_f32 v[82:83], v[48:49], v[82:83], v[88:89] op_sel:[1,0,0] op_sel_hi:[0,0,1] neg_lo:[0,0,1] neg_hi:[0,0,1]
	v_mov_b32_e32 v65, v87
	v_pk_mov_b32 v[88:89], v[86:87], v[90:91] op_sel:[1,0]
	v_mov_b32_e32 v109, v93
	v_pk_mov_b32 v[110:111], v[92:93], v[102:103] op_sel:[1,0]
	v_cvt_pk_bf16_f32 v62, v87, v93
	v_pk_fma_f32 v[86:87], v[50:51], v[80:81], v[94:95] op_sel:[1,0,0] op_sel_hi:[0,0,1]
	v_pk_fma_f32 v[80:81], v[50:51], v[80:81], v[94:95] op_sel:[1,0,0] op_sel_hi:[0,0,1] neg_lo:[0,0,1] neg_hi:[0,0,1]
	v_pk_fma_f32 v[92:93], v[52:53], v[84:85], v[96:97] op_sel:[1,0,0] op_sel_hi:[0,0,1]
	v_pk_fma_f32 v[84:85], v[52:53], v[84:85], v[96:97] op_sel:[1,0,0] op_sel_hi:[0,0,1] neg_lo:[0,0,1] neg_hi:[0,0,1]
	v_pk_fma_f32 v[94:95], v[42:43], v[78:79], v[66:67] op_sel:[1,0,0] op_sel_hi:[0,0,1]
	v_pk_fma_f32 v[66:67], v[42:43], v[78:79], v[66:67] op_sel:[1,0,0] op_sel_hi:[0,0,1] neg_lo:[0,0,1] neg_hi:[0,0,1]
	v_pk_fma_f32 v[78:79], v[44:45], v[100:101], v[68:69] op_sel:[1,0,0] op_sel_hi:[0,0,1]
	v_pk_fma_f32 v[68:69], v[44:45], v[100:101], v[68:69] op_sel:[1,0,0] op_sel_hi:[0,0,1] neg_lo:[0,0,1] neg_hi:[0,0,1]
	v_pk_fma_f32 v[96:97], v[46:47], v[106:107], v[98:99] op_sel:[1,0,0] op_sel_hi:[0,0,1]
	v_pk_fma_f32 v[98:99], v[46:47], v[106:107], v[98:99] op_sel:[1,0,0] op_sel_hi:[0,0,1] neg_lo:[0,0,1] neg_hi:[0,0,1]
	v_mov_b32_e32 v64, v90
	v_cvt_pk_bf16_f32 v63, v81, v85
	v_mov_b32_e32 v120, v78
	v_mov_b32_e32 v121, v69
	v_pk_mov_b32 v[122:123], v[68:69], v[78:79] op_sel:[1,0]
	v_mov_b32_e32 v124, v96
	v_mov_b32_e32 v125, v99
	v_pk_mov_b32 v[126:127], v[98:99], v[96:97] op_sel:[1,0]
	v_mov_b32_e32 v108, v102
	v_mov_b32_e32 v100, v104
	v_mov_b32_e32 v101, v83
	v_pk_mul_f32 v[106:107], v[54:55], v[64:65]
	v_mov_b32_e32 v112, v86
	v_mov_b32_e32 v113, v81
	v_pk_mov_b32 v[114:115], v[80:81], v[86:87] op_sel:[1,0]
	v_mov_b32_e32 v116, v92
	v_mov_b32_e32 v117, v85
	v_pk_mov_b32 v[118:119], v[84:85], v[92:93] op_sel:[1,0]
	v_mov_b32_e32 v80, v94
	v_mov_b32_e32 v81, v67
	v_pk_mov_b32 v[84:85], v[66:67], v[94:95] op_sel:[1,0]
	v_cvt_pk_bf16_f32 v64, v67, v69
	v_pk_mov_b32 v[128:129], v[82:83], v[104:105] op_sel:[1,0]
	v_cvt_pk_bf16_f32 v65, v99, v83
	v_pk_mul_f32 v[82:83], v[44:45], v[120:121]
	v_mfma_f32_16x16x32_bf16 v[30:33], v[38:41], v[62:65], v[30:33]
	v_mul_f32_e64 v62, v46, v124
	v_mul_f32_e64 v63, v47, v125
	v_pk_mul_f32 v[44:45], v[44:45], v[122:123]
	v_pk_mul_f32 v[46:47], v[46:47], v[126:127]
	v_pk_mul_f32 v[108:109], v[56:57], v[108:109]
	v_cvt_pk_bf16_f32 v66, v90, v102
	v_cvt_pk_bf16_f32 v67, v86, v92
	v_cvt_pk_bf16_f32 v68, v94, v78
	v_pk_mul_f32 v[54:55], v[54:55], v[88:89]
	v_pk_mul_f32 v[56:57], v[56:57], v[110:111]
	v_mfma_f32_16x16x32_bf16 v[22:25], v[34:37], v[70:73], v[22:25]
	v_mul_f32_e64 v70, v48, v100
	v_mul_f32_e64 v71, v49, v101
	v_pk_mul_f32 v[72:73], v[50:51], v[112:113]
	v_pk_mul_f32 v[78:79], v[52:53], v[116:117]
	v_pk_mul_f32 v[80:81], v[42:43], v[80:81]
	v_pk_mul_f32 v[48:49], v[48:49], v[128:129]
	v_pk_mul_f32 v[50:51], v[50:51], v[114:115]
	v_pk_mul_f32 v[52:53], v[52:53], v[118:119]
	v_pk_mul_f32 v[42:43], v[42:43], v[84:85]
	v_sub_f32_e32 v44, v44, v45
	v_sub_f32_e32 v45, v46, v47
	v_cvt_pk_bf16_f32 v69, v96, v104
	v_sub_f32_e32 v54, v54, v55
	v_sub_f32_e32 v55, v56, v57
	v_sub_f32_e32 v48, v48, v49
	v_sub_f32_e32 v49, v50, v51
	v_sub_f32_e32 v50, v52, v53
	v_sub_f32_e32 v51, v42, v43
	v_cvt_pk_bf16_f32 v42, v54, v55
	v_cvt_pk_bf16_f32 v43, v49, v50
	v_cvt_pk_bf16_f32 v44, v51, v44
	v_cvt_pk_bf16_f32 v45, v45, v48
	v_add_f32_e32 v61, v106, v107
	v_mfma_f32_16x16x32_bf16 v[26:29], v[38:41], v[42:45], v[26:29]
	v_add_f32_e32 v40, v82, v83
	v_add_f32_e32 v41, v62, v63
	v_add_f32_e32 v86, v108, v109
	v_add_f32_e32 v56, v70, v71
	v_add_f32_e32 v57, v72, v73
	v_add_f32_e32 v64, v78, v79
	v_add_f32_e32 v65, v80, v81
	v_mfma_f32_16x16x32_bf16 v[14:17], v[34:37], v[74:77], v[14:17]
	v_cvt_pk_bf16_f32 v38, v61, v86
	v_cvt_pk_bf16_f32 v39, v57, v64
	v_cvt_pk_bf16_f32 v40, v65, v40
	v_mfma_f32_16x16x32_bf16 v[30:33], v[34:37], v[66:69], v[30:33]
	v_cvt_pk_bf16_f32 v41, v41, v56
	s_mov_b32 s9, 1
	s_and_b64 vcc, exec, s[6:7]
	v_mfma_f32_16x16x32_bf16 v[26:29], v[34:37], v[38:41], v[26:29]
	s_mov_b64 s[6:7], 0
	s_cbranch_vccnz .LBB0_882
; __device__ __forceinline__ unsigned pk2(float lo, float hi) { unsigned r; asm volatile("v_cvt_pk_bf16_f32 %0, %1, %2" : "=v"(r) : "v"(lo), "v"(hi)); return r; }
; __device__ __forceinline__ float geluf_(float x) { return 0.5f * x * (1.f + tanhf(0.7978845608028654f * (x + 0.044715f * x * x * x))); }
; __device__ __forceinline__ void ph_s5_out(unsigned char* lds_, const bf16_t* Z, const bf16_t* TZB, const bf16_t* CQ, const float2* LP, const float* SLOC, const float* lamT, bf16_t* YG, int nrct, int u0, int ustep) { PH_IDS;
;     ...
; #pragma unroll
;         for (int i = 0; i < 8; ++i) { const int t = wid * 8 + i;
;             fa::u32x2 w; w.x = fa::pk2(geluf_(acc8[i][0]), geluf_(acc8[i][1])); w.y = fa::pk2(geluf_(acc8[i][2]), geluf_(acc8[i][3]));
;             *(fa::u32x2*)(YG + ((size_t)(rcbase + c16) * 64 + t) * ZW + C_S5 + g * 16 + 4 * kq) = w; }
	s_nop 5
	v_mul_f32_e32 v34, 0x3d372713, v26
	v_mul_f32_e32 v34, v26, v34
	v_fma_f32 v34, v26, v34, v26
	v_mul_f32_e32 v34, 0x3f4c422a, v34
	v_mul_f32_e32 v35, 0x4038aa3b, v34
	v_exp_f32_e32 v35, v35
	s_nop 0
	v_add_f32_e32 v35, 1.0, v35
	v_rcp_f32_e32 v35, v35
	s_nop 0
	v_fma_f32 v35, v35, -2.0, 1.0
	v_mul_f32_e32 v36, 0x3d372713, v27
	v_mul_f32_e32 v36, v27, v36
	v_fma_f32 v36, v27, v36, v27
	v_mul_f32_e32 v36, 0x3f4c422a, v36
	v_mul_f32_e32 v37, 0x4038aa3b, v36
	v_exp_f32_e32 v37, v37
	s_nop 0
	v_add_f32_e32 v37, 1.0, v37
	v_rcp_f32_e32 v37, v37
	s_nop 0
	v_fma_f32 v37, v37, -2.0, 1.0
	v_bfi_b32 v34, s91, v35, v34
	v_mul_f32_e32 v26, 0.5, v26
	v_add_f32_e32 v34, 1.0, v34
	v_mul_f32_e32 v26, v26, v34
	v_bfi_b32 v34, s91, v37, v36
	v_mul_f32_e32 v27, 0.5, v27
	v_add_f32_e32 v34, 1.0, v34
	v_mul_f32_e32 v27, v27, v34
	v_cvt_pk_bf16_f32 v34, v26, v27
	v_mul_f32_e32 v26, 0x3d372713, v28
	v_mul_f32_e32 v26, v28, v26
	v_fma_f32 v26, v28, v26, v28
	v_mul_f32_e32 v26, 0x3f4c422a, v26
	v_mul_f32_e32 v27, 0x4038aa3b, v26
	v_exp_f32_e32 v27, v27
	s_nop 0
	v_add_f32_e32 v27, 1.0, v27
	v_rcp_f32_e32 v27, v27
	s_nop 0
	v_fma_f32 v27, v27, -2.0, 1.0
	v_mul_f32_e32 v35, 0x3d372713, v29
	v_mul_f32_e32 v35, v29, v35
	v_fma_f32 v35, v29, v35, v29
	v_mul_f32_e32 v35, 0x3f4c422a, v35
	v_mul_f32_e32 v36, 0x4038aa3b, v35
	v_exp_f32_e32 v36, v36
	s_nop 0
	v_add_f32_e32 v36, 1.0, v36
	v_rcp_f32_e32 v36, v36
	s_nop 0
	v_fma_f32 v36, v36, -2.0, 1.0
	v_bfi_b32 v26, s91, v27, v26
	v_mul_f32_e32 v28, 0.5, v28
	v_add_f32_e32 v26, 1.0, v26
	v_bfi_b32 v35, s91, v36, v35
	v_mul_f32_e32 v28, v28, v26
	v_or_b32_e32 v26, s51, v168
	s_add_u32 s6, s76, 0x4c00000
	v_mul_f32_e32 v29, 0.5, v29
	v_add_f32_e32 v35, 1.0, v35
	v_lshlrev_b32_e32 v26, 6, v26
	v_mov_b32_e32 v27, v130
	s_addc_u32 s7, s77, 0
	v_mul_f32_e32 v29, v29, v35
	s_ashr_i32 s5, s4, 31
	v_cvt_pk_bf16_f32 v35, v28, v29
	v_lshl_add_u64 v[28:29], s[4:5], 0, v[26:27]
	v_lshlrev_b64 v[28:29], 12, v[28:29]
	v_lshl_add_u64 v[28:29], s[6:7], 0, v[28:29]
	s_lshl_b32 s56, s56, 1
	v_lshl_add_u64 v[28:29], v[28:29], 0, s[56:57]
	v_mov_b32_e32 v59, v130
	v_lshl_add_u64 v[28:29], v[28:29], 0, v[58:59]
	global_store_dwordx2 v[28:29], v[34:35], off offset:320
	v_mul_f32_e32 v28, 0x3d372713, v30
	v_mul_f32_e32 v28, v30, v28
	v_fma_f32 v28, v30, v28, v30
	v_mul_f32_e32 v28, 0x3f4c422a, v28
	v_mul_f32_e32 v29, 0x4038aa3b, v28
	v_exp_f32_e32 v29, v29
	s_nop 0
	v_add_f32_e32 v29, 1.0, v29
	v_rcp_f32_e32 v29, v29
	s_nop 0
	v_fma_f32 v29, v29, -2.0, 1.0
	v_mul_f32_e32 v34, 0x3d372713, v31
	v_mul_f32_e32 v34, v31, v34
	v_fma_f32 v34, v31, v34, v31
	v_mul_f32_e32 v34, 0x3f4c422a, v34
	v_mul_f32_e32 v35, 0x4038aa3b, v34
	v_exp_f32_e32 v35, v35
	s_nop 0
	v_add_f32_e32 v35, 1.0, v35
	v_rcp_f32_e32 v35, v35
	s_nop 0
	v_fma_f32 v35, v35, -2.0, 1.0
	v_bfi_b32 v28, s91, v29, v28
	v_mul_f32_e32 v30, 0.5, v30
	v_add_f32_e32 v28, 1.0, v28
	v_mul_f32_e32 v28, v30, v28
	v_bfi_b32 v30, s91, v35, v34
	v_mul_f32_e32 v29, 0.5, v31
	v_add_f32_e32 v30, 1.0, v30
	v_mul_f32_e32 v29, v29, v30
	v_cvt_pk_bf16_f32 v30, v28, v29
	v_mul_f32_e32 v28, 0x3d372713, v32
	v_mul_f32_e32 v28, v32, v28
	v_fma_f32 v28, v32, v28, v32
	v_mul_f32_e32 v28, 0x3f4c422a, v28
	v_mul_f32_e32 v29, 0x4038aa3b, v28
	v_exp_f32_e32 v29, v29
	s_nop 0
	v_add_f32_e32 v29, 1.0, v29
	v_rcp_f32_e32 v29, v29
	s_nop 0
	v_fma_f32 v29, v29, -2.0, 1.0
	v_mul_f32_e32 v31, 0x3d372713, v33
	v_mul_f32_e32 v31, v33, v31
	v_fma_f32 v31, v33, v31, v33
	v_mul_f32_e32 v31, 0x3f4c422a, v31
	v_mul_f32_e32 v34, 0x4038aa3b, v31
	v_exp_f32_e32 v34, v34
	s_nop 0
	v_add_f32_e32 v34, 1.0, v34
	v_rcp_f32_e32 v34, v34
	s_nop 0
	v_fma_f32 v34, v34, -2.0, 1.0
	v_bfi_b32 v28, s91, v29, v28
	v_bfi_b32 v31, s91, v34, v31
	v_mul_f32_e32 v32, 0.5, v32
	v_add_f32_e32 v28, 1.0, v28
	s_or_b32 s8, s4, 1
	v_mul_f32_e32 v29, 0.5, v33
	v_add_f32_e32 v31, 1.0, v31
	v_mul_f32_e32 v28, v32, v28
	v_mul_f32_e32 v29, v29, v31
	s_ashr_i32 s9, s8, 31
	v_cvt_pk_bf16_f32 v31, v28, v29
	v_lshl_add_u64 v[28:29], s[8:9], 0, v[26:27]
	v_lshlrev_b64 v[28:29], 12, v[28:29]
	v_lshlrev_b32_e32 v35, 2, v131
	v_lshl_add_u64 v[28:29], s[6:7], 0, v[28:29]
	v_lshl_add_u64 v[32:33], v[28:29], 0, s[56:57]
	v_lshlrev_b32_e32 v28, 1, v35
	v_mov_b32_e32 v29, v130
	v_lshl_add_u64 v[32:33], v[32:33], 0, v[28:29]
	v_mul_f32_e32 v29, 0x3d372713, v14
	v_mul_f32_e32 v29, v14, v29
	v_fma_f32 v29, v14, v29, v14
	v_mul_f32_e32 v29, 0x3f4c422a, v29
	global_store_dwordx2 v[32:33], v[30:31], off offset:320
	v_mul_f32_e32 v30, 0x4038aa3b, v29
	v_exp_f32_e32 v30, v30
	s_nop 0
	v_add_f32_e32 v30, 1.0, v30
	v_rcp_f32_e32 v30, v30
	s_nop 0
	v_fma_f32 v30, v30, -2.0, 1.0
	v_mul_f32_e32 v31, 0x3d372713, v15
	v_mul_f32_e32 v31, v15, v31
	v_fma_f32 v31, v15, v31, v15
	v_mul_f32_e32 v31, 0x3f4c422a, v31
	v_mul_f32_e32 v32, 0x4038aa3b, v31
	v_exp_f32_e32 v32, v32
	s_nop 0
	v_add_f32_e32 v32, 1.0, v32
	v_rcp_f32_e32 v32, v32
	s_nop 0
	v_fma_f32 v32, v32, -2.0, 1.0
	v_bfi_b32 v29, s91, v30, v29
	v_mul_f32_e32 v14, 0.5, v14
	v_add_f32_e32 v29, 1.0, v29
	v_mul_f32_e32 v14, v14, v29
	v_bfi_b32 v29, s91, v32, v31
	v_mul_f32_e32 v15, 0.5, v15
	v_add_f32_e32 v29, 1.0, v29
	v_mul_f32_e32 v15, v15, v29
	v_cvt_pk_bf16_f32 v14, v14, v15
	v_mul_f32_e32 v15, 0x3d372713, v16
	v_mul_f32_e32 v15, v16, v15
	v_fma_f32 v15, v16, v15, v16
	v_mul_f32_e32 v15, 0x3f4c422a, v15
	v_mul_f32_e32 v29, 0x4038aa3b, v15
	v_exp_f32_e32 v29, v29
	s_nop 0
	v_add_f32_e32 v29, 1.0, v29
	v_rcp_f32_e32 v29, v29
	s_nop 0
	v_fma_f32 v29, v29, -2.0, 1.0
	v_mul_f32_e32 v30, 0x3d372713, v17
	v_mul_f32_e32 v30, v17, v30
	v_fma_f32 v30, v17, v30, v17
	v_mul_f32_e32 v30, 0x3f4c422a, v30
	v_mul_f32_e32 v31, 0x4038aa3b, v30
; __device__ __forceinline__ unsigned pk2(float lo, float hi) { unsigned r; asm volatile("v_cvt_pk_bf16_f32 %0, %1, %2" : "=v"(r) : "v"(lo), "v"(hi)); return r; }
; __device__ __forceinline__ float geluf_(float x) { return 0.5f * x * (1.f + tanhf(0.7978845608028654f * (x + 0.044715f * x * x * x))); }
; __device__ __forceinline__ void ph_s5_out(unsigned char* lds_, const bf16_t* Z, const bf16_t* TZB, const bf16_t* CQ, const float2* LP, const float* SLOC, const float* lamT, bf16_t* YG, int nrct, int u0, int ustep) { PH_IDS;
;     ...
; #pragma unroll
;         for (int i = 0; i < 8; ++i) { const int t = wid * 8 + i;
;             fa::u32x2 w; w.x = fa::pk2(geluf_(acc8[i][0]), geluf_(acc8[i][1])); w.y = fa::pk2(geluf_(acc8[i][2]), geluf_(acc8[i][3]));
;             *(fa::u32x2*)(YG + ((size_t)(rcbase + c16) * 64 + t) * ZW + C_S5 + g * 16 + 4 * kq) = w; }
	v_exp_f32_e32 v31, v31
	s_nop 0
	v_add_f32_e32 v31, 1.0, v31
	v_rcp_f32_e32 v31, v31
	s_nop 0
	v_fma_f32 v31, v31, -2.0, 1.0
	v_bfi_b32 v15, s91, v29, v15
	v_mul_f32_e32 v16, 0.5, v16
	v_add_f32_e32 v15, 1.0, v15
	v_mul_f32_e32 v15, v16, v15
	v_mul_f32_e32 v16, 0.5, v17
	v_bfi_b32 v17, s91, v31, v30
	s_or_b32 s8, s4, 2
	v_add_f32_e32 v17, 1.0, v17
	v_mul_f32_e32 v16, v16, v17
	s_ashr_i32 s9, s8, 31
	v_cvt_pk_bf16_f32 v15, v15, v16
	v_lshl_add_u64 v[16:17], s[8:9], 0, v[26:27]
	v_lshlrev_b64 v[16:17], 12, v[16:17]
	v_lshl_add_u64 v[16:17], s[6:7], 0, v[16:17]
	v_lshl_add_u64 v[16:17], v[16:17], 0, s[56:57]
	v_mov_b32_e32 v29, v130
	v_lshl_add_u64 v[16:17], v[16:17], 0, v[28:29]
	global_store_dwordx2 v[16:17], v[14:15], off offset:320
	v_mul_f32_e32 v14, 0x3d372713, v22
	v_mul_f32_e32 v14, v22, v14
	v_fma_f32 v14, v22, v14, v22
	v_mul_f32_e32 v14, 0x3f4c422a, v14
	v_mul_f32_e32 v15, 0x4038aa3b, v14
	v_exp_f32_e32 v15, v15
	s_nop 0
	v_add_f32_e32 v15, 1.0, v15
	v_rcp_f32_e32 v15, v15
	s_nop 0
	v_fma_f32 v15, v15, -2.0, 1.0
	v_mul_f32_e32 v16, 0x3d372713, v23
	v_mul_f32_e32 v16, v23, v16
	v_fma_f32 v16, v23, v16, v23
	v_mul_f32_e32 v16, 0x3f4c422a, v16
	v_mul_f32_e32 v17, 0x4038aa3b, v16
	v_exp_f32_e32 v17, v17
	s_nop 0
	v_add_f32_e32 v17, 1.0, v17
	v_rcp_f32_e32 v17, v17
	s_nop 0
	v_fma_f32 v17, v17, -2.0, 1.0
	v_bfi_b32 v14, s91, v15, v14
	v_bfi_b32 v16, s91, v17, v16
	v_mul_f32_e32 v22, 0.5, v22
	v_add_f32_e32 v14, 1.0, v14
	v_mul_f32_e32 v15, 0.5, v23
	v_add_f32_e32 v16, 1.0, v16
	v_mul_f32_e32 v14, v22, v14
	v_mul_f32_e32 v15, v15, v16
	v_cvt_pk_bf16_f32 v14, v14, v15
	v_mul_f32_e32 v15, 0x3d372713, v24
	v_mul_f32_e32 v15, v24, v15
	v_fma_f32 v15, v24, v15, v24
	v_mul_f32_e32 v15, 0x3f4c422a, v15
	v_mul_f32_e32 v16, 0x4038aa3b, v15
	v_exp_f32_e32 v16, v16
	s_nop 0
	v_add_f32_e32 v16, 1.0, v16
	v_rcp_f32_e32 v16, v16
	s_nop 0
	v_fma_f32 v16, v16, -2.0, 1.0
	v_mul_f32_e32 v17, 0x3d372713, v25
	v_mul_f32_e32 v17, v25, v17
	v_fma_f32 v17, v25, v17, v25
	v_mul_f32_e32 v17, 0x3f4c422a, v17
	v_mul_f32_e32 v22, 0x4038aa3b, v17
	v_exp_f32_e32 v22, v22
	s_nop 0
	v_add_f32_e32 v22, 1.0, v22
	v_rcp_f32_e32 v22, v22
	s_nop 0
	v_fma_f32 v22, v22, -2.0, 1.0
	v_bfi_b32 v15, s91, v16, v15
	v_bfi_b32 v17, s91, v22, v17
	v_mul_f32_e32 v23, 0.5, v24
	v_add_f32_e32 v15, 1.0, v15
	s_or_b32 s8, s4, 3
	v_mul_f32_e32 v16, 0.5, v25
	v_add_f32_e32 v17, 1.0, v17
	v_mul_f32_e32 v15, v23, v15
	v_mul_f32_e32 v16, v16, v17
	s_ashr_i32 s9, s8, 31
	v_cvt_pk_bf16_f32 v15, v15, v16
	v_lshl_add_u64 v[16:17], s[8:9], 0, v[26:27]
	v_lshlrev_b64 v[16:17], 12, v[16:17]
	v_lshl_add_u64 v[16:17], s[6:7], 0, v[16:17]
	v_lshl_add_u64 v[16:17], v[16:17], 0, s[56:57]
	v_mov_b32_e32 v29, v130
	v_lshl_add_u64 v[16:17], v[16:17], 0, v[28:29]
	global_store_dwordx2 v[16:17], v[14:15], off offset:320
	v_mul_f32_e32 v14, 0x3d372713, v6
	v_mul_f32_e32 v14, v6, v14
	v_fma_f32 v14, v6, v14, v6
	v_mul_f32_e32 v14, 0x3f4c422a, v14
	v_mul_f32_e32 v15, 0x4038aa3b, v14
	v_exp_f32_e32 v15, v15
	s_nop 0
	v_add_f32_e32 v15, 1.0, v15
	v_rcp_f32_e32 v15, v15
	s_nop 0
	v_fma_f32 v15, v15, -2.0, 1.0
	v_mul_f32_e32 v16, 0x3d372713, v7
	v_mul_f32_e32 v16, v7, v16
	v_fma_f32 v16, v7, v16, v7
	v_mul_f32_e32 v16, 0x3f4c422a, v16
	v_mul_f32_e32 v17, 0x4038aa3b, v16
	v_exp_f32_e32 v17, v17
	s_nop 0
	v_add_f32_e32 v17, 1.0, v17
	v_rcp_f32_e32 v17, v17
	s_nop 0
	v_fma_f32 v17, v17, -2.0, 1.0
	v_bfi_b32 v14, s91, v15, v14
	v_mul_f32_e32 v6, 0.5, v6
	v_add_f32_e32 v14, 1.0, v14
	v_mul_f32_e32 v6, v6, v14
	v_bfi_b32 v14, s91, v17, v16
	v_mul_f32_e32 v7, 0.5, v7
	v_add_f32_e32 v14, 1.0, v14
	v_mul_f32_e32 v7, v7, v14
	v_cvt_pk_bf16_f32 v6, v6, v7
	v_mul_f32_e32 v7, 0x3d372713, v8
	v_mul_f32_e32 v7, v8, v7
	v_fma_f32 v7, v8, v7, v8
	v_mul_f32_e32 v7, 0x3f4c422a, v7
	v_mul_f32_e32 v14, 0x4038aa3b, v7
	v_exp_f32_e32 v14, v14
	s_nop 0
	v_add_f32_e32 v14, 1.0, v14
	v_rcp_f32_e32 v14, v14
	s_nop 0
	v_fma_f32 v14, v14, -2.0, 1.0
	v_mul_f32_e32 v15, 0x3d372713, v9
	v_mul_f32_e32 v15, v9, v15
	v_fma_f32 v15, v9, v15, v9
	v_mul_f32_e32 v15, 0x3f4c422a, v15
	v_mul_f32_e32 v16, 0x4038aa3b, v15
	v_exp_f32_e32 v16, v16
	s_nop 0
	v_add_f32_e32 v16, 1.0, v16
	v_rcp_f32_e32 v16, v16
	s_nop 0
	v_fma_f32 v16, v16, -2.0, 1.0
	v_bfi_b32 v7, s91, v14, v7
	v_mul_f32_e32 v8, 0.5, v8
	v_add_f32_e32 v7, 1.0, v7
	v_mul_f32_e32 v7, v8, v7
	v_mul_f32_e32 v8, 0.5, v9
	v_bfi_b32 v9, s91, v16, v15
	s_or_b32 s8, s4, 4
	v_add_f32_e32 v9, 1.0, v9
	v_mul_f32_e32 v8, v8, v9
	s_ashr_i32 s9, s8, 31
	v_cvt_pk_bf16_f32 v7, v7, v8
	v_lshl_add_u64 v[8:9], s[8:9], 0, v[26:27]
	v_lshlrev_b64 v[8:9], 12, v[8:9]
	v_lshl_add_u64 v[8:9], s[6:7], 0, v[8:9]
	v_lshl_add_u64 v[8:9], v[8:9], 0, s[56:57]
	v_mov_b32_e32 v29, v130
	v_lshl_add_u64 v[8:9], v[8:9], 0, v[28:29]
	global_store_dwordx2 v[8:9], v[6:7], off offset:320
	v_mul_f32_e32 v6, 0x3d372713, v18
	v_mul_f32_e32 v6, v18, v6
	v_fma_f32 v6, v18, v6, v18
	v_mul_f32_e32 v6, 0x3f4c422a, v6
	v_mul_f32_e32 v7, 0x4038aa3b, v6
	v_exp_f32_e32 v7, v7
	s_nop 0
	v_add_f32_e32 v7, 1.0, v7
	v_rcp_f32_e32 v7, v7
	s_nop 0
	v_fma_f32 v7, v7, -2.0, 1.0
	v_mul_f32_e32 v8, 0x3d372713, v19
	v_mul_f32_e32 v8, v19, v8
	v_fma_f32 v8, v19, v8, v19
	v_mul_f32_e32 v8, 0x3f4c422a, v8
	v_mul_f32_e32 v9, 0x4038aa3b, v8
	v_exp_f32_e32 v9, v9
	s_nop 0
	v_add_f32_e32 v9, 1.0, v9
; __device__ __forceinline__ unsigned pk2(float lo, float hi) { unsigned r; asm volatile("v_cvt_pk_bf16_f32 %0, %1, %2" : "=v"(r) : "v"(lo), "v"(hi)); return r; }
; __device__ __forceinline__ float geluf_(float x) { return 0.5f * x * (1.f + tanhf(0.7978845608028654f * (x + 0.044715f * x * x * x))); }
; __device__ __forceinline__ void ph_s5_out(unsigned char* lds_, const bf16_t* Z, const bf16_t* TZB, const bf16_t* CQ, const float2* LP, const float* SLOC, const float* lamT, bf16_t* YG, int nrct, int u0, int ustep) { PH_IDS;
;     ...
; #pragma unroll
;         for (int i = 0; i < 8; ++i) { const int t = wid * 8 + i;
;             fa::u32x2 w; w.x = fa::pk2(geluf_(acc8[i][0]), geluf_(acc8[i][1])); w.y = fa::pk2(geluf_(acc8[i][2]), geluf_(acc8[i][3]));
;             *(fa::u32x2*)(YG + ((size_t)(rcbase + c16) * 64 + t) * ZW + C_S5 + g * 16 + 4 * kq) = w; }
	v_rcp_f32_e32 v9, v9
	s_nop 0
	v_fma_f32 v9, v9, -2.0, 1.0
	v_bfi_b32 v6, s91, v7, v6
	v_bfi_b32 v8, s91, v9, v8
	v_mul_f32_e32 v14, 0.5, v18
	v_add_f32_e32 v6, 1.0, v6
	v_mul_f32_e32 v7, 0.5, v19
	v_add_f32_e32 v8, 1.0, v8
	v_mul_f32_e32 v6, v14, v6
	v_mul_f32_e32 v7, v7, v8
	v_cvt_pk_bf16_f32 v6, v6, v7
	v_mul_f32_e32 v7, 0x3d372713, v20
	v_mul_f32_e32 v7, v20, v7
	v_fma_f32 v7, v20, v7, v20
	v_mul_f32_e32 v7, 0x3f4c422a, v7
	v_mul_f32_e32 v8, 0x4038aa3b, v7
	v_exp_f32_e32 v8, v8
	s_nop 0
	v_add_f32_e32 v8, 1.0, v8
	v_rcp_f32_e32 v8, v8
	s_nop 0
	v_fma_f32 v8, v8, -2.0, 1.0
	v_mul_f32_e32 v9, 0x3d372713, v21
	v_mul_f32_e32 v9, v21, v9
	v_fma_f32 v9, v21, v9, v21
	v_mul_f32_e32 v9, 0x3f4c422a, v9
	v_mul_f32_e32 v14, 0x4038aa3b, v9
	v_exp_f32_e32 v14, v14
	s_nop 0
	v_add_f32_e32 v14, 1.0, v14
	v_rcp_f32_e32 v14, v14
	s_nop 0
	v_fma_f32 v14, v14, -2.0, 1.0
	v_bfi_b32 v7, s91, v8, v7
	v_bfi_b32 v9, s91, v14, v9
	v_mul_f32_e32 v15, 0.5, v20
	v_add_f32_e32 v7, 1.0, v7
	s_or_b32 s8, s4, 5
	v_mul_f32_e32 v8, 0.5, v21
	v_add_f32_e32 v9, 1.0, v9
	v_mul_f32_e32 v7, v15, v7
	v_mul_f32_e32 v8, v8, v9
	s_ashr_i32 s9, s8, 31
	v_cvt_pk_bf16_f32 v7, v7, v8
	v_lshl_add_u64 v[8:9], s[8:9], 0, v[26:27]
	v_lshlrev_b64 v[8:9], 12, v[8:9]
	v_lshl_add_u64 v[8:9], s[6:7], 0, v[8:9]
	v_lshl_add_u64 v[8:9], v[8:9], 0, s[56:57]
	v_mov_b32_e32 v29, v130
	v_lshl_add_u64 v[8:9], v[8:9], 0, v[28:29]
	global_store_dwordx2 v[8:9], v[6:7], off offset:320
	v_mul_f32_e32 v6, 0x3d372713, v2
	v_mul_f32_e32 v6, v2, v6
	v_fma_f32 v6, v2, v6, v2
	v_mul_f32_e32 v6, 0x3f4c422a, v6
	v_mul_f32_e32 v7, 0x4038aa3b, v6
	v_exp_f32_e32 v7, v7
	s_nop 0
	v_add_f32_e32 v7, 1.0, v7
	v_rcp_f32_e32 v7, v7
	s_nop 0
	v_fma_f32 v7, v7, -2.0, 1.0
	v_mul_f32_e32 v8, 0x3d372713, v3
	v_mul_f32_e32 v8, v3, v8
	v_fma_f32 v8, v3, v8, v3
	v_mul_f32_e32 v8, 0x3f4c422a, v8
	v_mul_f32_e32 v9, 0x4038aa3b, v8
	v_exp_f32_e32 v9, v9
	s_nop 0
	v_add_f32_e32 v9, 1.0, v9
	v_rcp_f32_e32 v9, v9
	s_nop 0
	v_fma_f32 v9, v9, -2.0, 1.0
	v_bfi_b32 v6, s91, v7, v6
	v_mul_f32_e32 v2, 0.5, v2
	v_add_f32_e32 v6, 1.0, v6
	v_mul_f32_e32 v2, v2, v6
	v_bfi_b32 v6, s91, v9, v8
	v_mul_f32_e32 v3, 0.5, v3
	v_add_f32_e32 v6, 1.0, v6
	v_mul_f32_e32 v3, v3, v6
	v_cvt_pk_bf16_f32 v2, v2, v3
	v_mul_f32_e32 v3, 0x3d372713, v4
	v_mul_f32_e32 v3, v4, v3
	v_fma_f32 v3, v4, v3, v4
	v_mul_f32_e32 v3, 0x3f4c422a, v3
	v_mul_f32_e32 v6, 0x4038aa3b, v3
	v_exp_f32_e32 v6, v6
	s_nop 0
	v_add_f32_e32 v6, 1.0, v6
	v_rcp_f32_e32 v6, v6
	s_nop 0
	v_fma_f32 v6, v6, -2.0, 1.0
	v_mul_f32_e32 v7, 0x3d372713, v5
	v_mul_f32_e32 v7, v5, v7
	v_fma_f32 v7, v5, v7, v5
	v_mul_f32_e32 v7, 0x3f4c422a, v7
	v_mul_f32_e32 v8, 0x4038aa3b, v7
	v_exp_f32_e32 v8, v8
	s_nop 0
	v_add_f32_e32 v8, 1.0, v8
	v_rcp_f32_e32 v8, v8
	s_nop 0
	v_fma_f32 v8, v8, -2.0, 1.0
	v_bfi_b32 v3, s91, v6, v3
	v_mul_f32_e32 v4, 0.5, v4
	v_add_f32_e32 v3, 1.0, v3
	v_mul_f32_e32 v3, v4, v3
	v_mul_f32_e32 v4, 0.5, v5
	v_bfi_b32 v5, s91, v8, v7
	s_or_b32 s8, s4, 6
	v_add_f32_e32 v5, 1.0, v5
	v_mul_f32_e32 v4, v4, v5
	s_ashr_i32 s9, s8, 31
	v_cvt_pk_bf16_f32 v3, v3, v4
	v_lshl_add_u64 v[4:5], s[8:9], 0, v[26:27]
	v_lshlrev_b64 v[4:5], 12, v[4:5]
	v_lshl_add_u64 v[4:5], s[6:7], 0, v[4:5]
	v_lshl_add_u64 v[4:5], v[4:5], 0, s[56:57]
	v_mov_b32_e32 v29, v130
	v_lshl_add_u64 v[4:5], v[4:5], 0, v[28:29]
	global_store_dwordx2 v[4:5], v[2:3], off offset:320
	v_mul_f32_e32 v2, 0x3d372713, v10
	v_mul_f32_e32 v2, v10, v2
	v_fma_f32 v2, v10, v2, v10
	v_mul_f32_e32 v2, 0x3f4c422a, v2
	v_mul_f32_e32 v3, 0x4038aa3b, v2
	v_exp_f32_e32 v3, v3
	s_nop 0
	v_add_f32_e32 v3, 1.0, v3
	v_rcp_f32_e32 v3, v3
	s_nop 0
	v_fma_f32 v3, v3, -2.0, 1.0
	v_mul_f32_e32 v4, 0x3d372713, v11
	v_mul_f32_e32 v4, v11, v4
	v_fma_f32 v4, v11, v4, v11
	v_mul_f32_e32 v4, 0x3f4c422a, v4
	v_mul_f32_e32 v5, 0x4038aa3b, v4
	v_exp_f32_e32 v5, v5
	s_nop 0
	v_add_f32_e32 v5, 1.0, v5
	v_rcp_f32_e32 v5, v5
	s_nop 0
	v_fma_f32 v5, v5, -2.0, 1.0
	v_bfi_b32 v2, s91, v3, v2
	v_bfi_b32 v4, s91, v5, v4
	v_mul_f32_e32 v6, 0.5, v10
	v_add_f32_e32 v2, 1.0, v2
	v_mul_f32_e32 v3, 0.5, v11
	v_add_f32_e32 v4, 1.0, v4
	v_mul_f32_e32 v2, v6, v2
	v_mul_f32_e32 v3, v3, v4
	v_cvt_pk_bf16_f32 v2, v2, v3
	v_mul_f32_e32 v3, 0x3d372713, v12
	v_mul_f32_e32 v3, v12, v3
	v_fma_f32 v3, v12, v3, v12
	v_mul_f32_e32 v3, 0x3f4c422a, v3
	v_mul_f32_e32 v4, 0x4038aa3b, v3
	v_exp_f32_e32 v4, v4
	s_nop 0
	v_add_f32_e32 v4, 1.0, v4
	v_rcp_f32_e32 v4, v4
	s_nop 0
	v_fma_f32 v4, v4, -2.0, 1.0
	v_mul_f32_e32 v5, 0x3d372713, v13
	v_mul_f32_e32 v5, v13, v5
	v_fma_f32 v5, v13, v5, v13
	v_mul_f32_e32 v5, 0x3f4c422a, v5
	v_mul_f32_e32 v6, 0x4038aa3b, v5
	v_exp_f32_e32 v6, v6
	s_nop 0
	v_add_f32_e32 v6, 1.0, v6
	v_rcp_f32_e32 v6, v6
	s_nop 0
	v_fma_f32 v6, v6, -2.0, 1.0
	v_bfi_b32 v3, s91, v4, v3
	v_bfi_b32 v5, s91, v6, v5
	v_mul_f32_e32 v7, 0.5, v12
	v_add_f32_e32 v3, 1.0, v3
	s_or_b32 s4, s4, 7
	v_mul_f32_e32 v4, 0.5, v13
	v_add_f32_e32 v5, 1.0, v5
	v_mul_f32_e32 v3, v7, v3
	v_mul_f32_e32 v4, v4, v5
	s_ashr_i32 s5, s4, 31
	v_cvt_pk_bf16_f32 v3, v3, v4
	v_lshl_add_u64 v[4:5], s[4:5], 0, v[26:27]
	v_lshlrev_b64 v[4:5], 12, v[4:5]
	v_lshl_add_u64 v[4:5], s[6:7], 0, v[4:5]
	v_lshl_add_u64 v[4:5], v[4:5], 0, s[56:57]
	v_mov_b32_e32 v29, v130
	v_lshl_add_u64 v[4:5], v[4:5], 0, v[28:29]
	global_store_dwordx2 v[4:5], v[2:3], off offset:320
	s_barrier

; #define LAS __attribute__((address_space(3)))
; __device__ __forceinline__ void ph_s5_out(unsigned char* lds_, const bf16_t* Z, const bf16_t* TZB, const bf16_t* CQ, const float2* LP, const float* SLOC, const float* lamT, bf16_t* YG, int nrct, int u0, int ustep) { PH_IDS;
;     ...
;         {
; #pragma unroll
;             for (int d = 0; d < 2; ++d)
; #pragma unroll 1
;             for (int ph = 0; ph < 2; ++ph) {
;                 asm volatile("" ::: "memory");
;                 const bf16x8 cqr = *(const LAS bf16x8*)(sm + O_SL + 9216 + (c16 * 256 + 32 * (4 * d + ph) + 8 * kq) * 2), cqi = *(const LAS bf16x8*)(sm + O_SL + 9216 + (c16 * 256 + 32 * (4 * d + 2 + ph) + 8 * kq) * 2);
;                 const bf16x8 xre = *(const LAS bf16x8*)(xb + (4 * d + ph) * 64), xim = *(const LAS bf16x8*)(xb + (4 * d + 2 + ph) * 64);
;                 float yr[8], yi[8], lr[8], li[8];
; #pragma unroll
;                 for (int j = 0; j < 8; ++j) {
;                     const int p_ = 32 * ph + 8 * kq + j;
;                     const f32x2v l1 = *(const LAS f32x2v*)(sm + O_SL + (d * 64 + p_) * 8), ls = *(const LAS f32x2v*)(sm + O_SL + (128 + (wid * 2 + d) * 64 + p_) * 8);
;                     const float xr = __uint_as_float((unsigned)(unsigned short)xre[j] << 16), xi = __uint_as_float((unsigned)(unsigned short)xim[j] << 16);
;                     yr[j] = ls.x * xr - ls.y * xi; yi[j] = ls.x * xi + ls.y * xr; lr[j] = l1.x; li[j] = l1.y;
;                 }
; #pragma unroll
;                 for (int s8 = 0; s8 < 8; ++s8) {
;                     const int i = d == 0 ? s8 : 7 - s8;
;                     const bf16x8 bre = __builtin_bit_cast(bf16x8, pack8((f32x4){yr[0], yr[1], yr[2], yr[3]}, (f32x4){yr[4], yr[5], yr[6], yr[7]}));
;                     const bf16x8 bim = __builtin_bit_cast(bf16x8, pack8((f32x4){yi[0], yi[1], yi[2], yi[3]}, (f32x4){yi[4], yi[5], yi[6], yi[7]}));
;                     acc8[i] = __builtin_amdgcn_mfma_f32_16x16x32_bf16(cqr, bre, acc8[i], 0, 0, 0);
;                     acc8[i] = __builtin_amdgcn_mfma_f32_16x16x32_bf16(cqi, bim, acc8[i], 0, 0, 0);
;                     if (s8 < 7) {
; #pragma unroll
;                         for (int j = 0; j < 8; ++j) { const float a = yr[j], c = yi[j]; yr[j] = lr[j] * a - li[j] * c; yi[j] = lr[j] * c + li[j] * a; }
;                     }
;                 }
;             }
.LBB0_2829:
	s_lshl_b32 s8, s9, 6
	v_lshl_or_b32 v34, s9, 5, v58
	v_add_u32_e32 v35, s8, v60
	v_add_u32_e32 v42, s8, v59
	v_or_b32_e32 v45, 2, v34
	v_or_b32_e32 v46, 4, v34
	v_or_b32_e32 v47, 6, v34
	v_lshl_add_u32 v43, v34, 3, s88
	v_or_b32_e32 v44, s5, v34
	ds_read_b128 v[38:41], v35 offset:256
	ds_read_b128 v[34:37], v35 offset:384
	ds_read_b128 v[62:65], v42 offset:256
	ds_read_b128 v[66:69], v42 offset:384
	v_lshl_add_u32 v50, v45, 3, s88
	v_or_b32_e32 v42, s5, v45
	v_lshl_add_u32 v45, v46, 3, s88
	v_or_b32_e32 v46, s5, v46
	v_or_b32_e32 v51, s5, v47
	v_lshl_add_u32 v44, v44, 3, s88
	v_lshl_add_u32 v48, v47, 3, s88
	ds_read_b128 v[54:57], v43 offset:512
	ds_read_b128 v[70:73], v44
	v_lshl_add_u32 v78, v46, 3, s88
	v_lshl_add_u32 v82, v51, 3, s88
	v_lshl_add_u32 v61, v42, 3, s88
	ds_read_b128 v[42:45], v45 offset:512
	ds_read_b128 v[46:49], v48 offset:512
	ds_read_b128 v[50:53], v50 offset:512
	ds_read_b128 v[74:77], v61
	ds_read_b128 v[78:81], v78
	ds_read_b128 v[82:85], v82
	s_waitcnt lgkmcnt(8)
	v_lshlrev_b32_e32 v88, 16, v66
	v_and_b32_e32 v66, 0xffff0000, v66
	v_lshlrev_b32_e32 v86, 16, v62
	v_and_b32_e32 v62, 0xffff0000, v62
	v_lshlrev_b32_e32 v92, 16, v67
	v_and_b32_e32 v96, 0xffff0000, v67
	v_lshlrev_b32_e32 v100, 16, v68
	v_and_b32_e32 v68, 0xffff0000, v68
	v_lshlrev_b32_e32 v104, 16, v69
	v_and_b32_e32 v108, 0xffff0000, v69
	s_waitcnt lgkmcnt(6)
	v_pk_mul_f32 v[88:89], v[70:71], v[88:89] op_sel_hi:[1,0]
	v_pk_mul_f32 v[66:67], v[72:73], v[66:67] op_sel_hi:[1,0]
	v_lshlrev_b32_e32 v90, 16, v63
	v_and_b32_e32 v94, 0xffff0000, v63
	v_lshlrev_b32_e32 v98, 16, v64
	v_and_b32_e32 v64, 0xffff0000, v64
	v_lshlrev_b32_e32 v102, 16, v65
	v_and_b32_e32 v106, 0xffff0000, v65
	v_pk_fma_f32 v[110:111], v[70:71], v[86:87], v[88:89] op_sel:[1,0,0] op_sel_hi:[0,0,1]
	v_pk_fma_f32 v[70:71], v[70:71], v[86:87], v[88:89] op_sel:[1,0,0] op_sel_hi:[0,0,1] neg_lo:[0,0,1] neg_hi:[0,0,1]
	v_pk_fma_f32 v[86:87], v[72:73], v[62:63], v[66:67] op_sel:[1,0,0] op_sel_hi:[0,0,1]
	v_pk_fma_f32 v[62:63], v[72:73], v[62:63], v[66:67] op_sel:[1,0,0] op_sel_hi:[0,0,1] neg_lo:[0,0,1] neg_hi:[0,0,1]
	s_waitcnt lgkmcnt(2)
	v_pk_mul_f32 v[66:67], v[74:75], v[92:93] op_sel_hi:[1,0]
	v_pk_mul_f32 v[72:73], v[76:77], v[96:97] op_sel_hi:[1,0]
	s_waitcnt lgkmcnt(1)
	v_pk_mul_f32 v[88:89], v[78:79], v[100:101] op_sel_hi:[1,0]
	v_pk_mul_f32 v[68:69], v[80:81], v[68:69] op_sel_hi:[1,0]
	s_waitcnt lgkmcnt(0)
	v_pk_mul_f32 v[92:93], v[82:83], v[104:105] op_sel_hi:[1,0]
	v_pk_mul_f32 v[96:97], v[84:85], v[108:109] op_sel_hi:[1,0]
	v_mov_b32_e32 v100, v110
	v_mov_b32_e32 v101, v71
	v_pk_mov_b32 v[104:105], v[70:71], v[110:111] op_sel:[1,0]
	v_mul_f32_e32 v70, v55, v110
	v_mul_f32_e32 v108, v55, v71
	v_mov_b32_e32 v112, v86
	v_mov_b32_e32 v113, v63
	v_pk_mov_b32 v[114:115], v[62:63], v[86:87] op_sel:[1,0]
	v_mul_f32_e32 v116, v57, v86
	v_mul_f32_e32 v118, v57, v63
	v_pk_fma_f32 v[120:121], v[74:75], v[90:91], v[66:67] op_sel:[1,0,0] op_sel_hi:[0,0,1]
	v_pk_fma_f32 v[66:67], v[74:75], v[90:91], v[66:67] op_sel:[1,0,0] op_sel_hi:[0,0,1] neg_lo:[0,0,1] neg_hi:[0,0,1]
	v_pk_fma_f32 v[74:75], v[76:77], v[94:95], v[72:73] op_sel:[1,0,0] op_sel_hi:[0,0,1]
	v_pk_fma_f32 v[72:73], v[76:77], v[94:95], v[72:73] op_sel:[1,0,0] op_sel_hi:[0,0,1] neg_lo:[0,0,1] neg_hi:[0,0,1]
	v_pk_fma_f32 v[76:77], v[78:79], v[98:99], v[88:89] op_sel:[1,0,0] op_sel_hi:[0,0,1]
	v_pk_fma_f32 v[78:79], v[78:79], v[98:99], v[88:89] op_sel:[1,0,0] op_sel_hi:[0,0,1] neg_lo:[0,0,1] neg_hi:[0,0,1]
	v_pk_fma_f32 v[88:89], v[80:81], v[64:65], v[68:69] op_sel:[1,0,0] op_sel_hi:[0,0,1]
	v_pk_fma_f32 v[64:65], v[80:81], v[64:65], v[68:69] op_sel:[1,0,0] op_sel_hi:[0,0,1] neg_lo:[0,0,1] neg_hi:[0,0,1]
	v_pk_fma_f32 v[80:81], v[82:83], v[102:103], v[92:93] op_sel:[1,0,0] op_sel_hi:[0,0,1]
	v_pk_fma_f32 v[68:69], v[82:83], v[102:103], v[92:93] op_sel:[1,0,0] op_sel_hi:[0,0,1] neg_lo:[0,0,1] neg_hi:[0,0,1]
	v_pk_fma_f32 v[82:83], v[84:85], v[106:107], v[96:97] op_sel:[1,0,0] op_sel_hi:[0,0,1]
	v_pk_fma_f32 v[84:85], v[84:85], v[106:107], v[96:97] op_sel:[1,0,0] op_sel_hi:[0,0,1] neg_lo:[0,0,1] neg_hi:[0,0,1]
	v_cvt_pk_bf16_f32 v62, v71, v63
	v_pk_fma_f32 v[90:91], v[54:55], v[104:105], v[70:71] op_sel_hi:[1,1,0] neg_lo:[0,0,1] neg_hi:[0,0,1]
	v_pk_fma_f32 v[70:71], v[54:55], v[100:101], v[108:109] op_sel_hi:[1,1,0]
	v_pk_fma_f32 v[92:93], v[56:57], v[114:115], v[116:117] op_sel_hi:[1,1,0] neg_lo:[0,0,1] neg_hi:[0,0,1]
	v_pk_fma_f32 v[94:95], v[56:57], v[112:113], v[118:119] op_sel_hi:[1,1,0]
	v_mov_b32_e32 v96, v120
	v_mov_b32_e32 v97, v67
	v_pk_mov_b32 v[98:99], v[66:67], v[120:121] op_sel:[1,0]
	v_mul_f32_e32 v100, v51, v120
	v_mul_f32_e32 v102, v51, v67
	v_mov_b32_e32 v104, v74
	v_mov_b32_e32 v105, v73
	v_pk_mov_b32 v[106:107], v[72:73], v[74:75] op_sel:[1,0]
	v_cvt_pk_bf16_f32 v63, v67, v73
	v_mul_f32_e32 v72, v53, v74
	v_mul_f32_e32 v108, v53, v73
	v_mov_b32_e32 v112, v76
	v_mov_b32_e32 v113, v79
	v_pk_mov_b32 v[114:115], v[78:79], v[76:77] op_sel:[1,0]
	v_mul_f32_e32 v78, v43, v76
	v_mul_f32_e32 v116, v43, v79
	v_mov_b32_e32 v118, v88
	v_mov_b32_e32 v119, v65
	v_pk_mov_b32 v[122:123], v[64:65], v[88:89] op_sel:[1,0]
	v_cvt_pk_bf16_f32 v64, v79, v65
	v_mul_f32_e32 v126, v45, v65
	v_mov_b32_e32 v128, v80
	v_mov_b32_e32 v129, v69
	v_pk_mov_b32 v[132:133], v[68:69], v[80:81] op_sel:[1,0]
	v_mul_f32_e32 v136, v47, v69
	v_mov_b32_e32 v138, v82
	v_mov_b32_e32 v139, v85
	v_cvt_pk_bf16_f32 v65, v69, v85
	v_cvt_pk_bf16_f32 v66, v110, v86
	v_cvt_pk_bf16_f32 v67, v120, v74
	v_cvt_pk_bf16_f32 v68, v76, v88
	v_mul_f32_e32 v76, v49, v85
	v_mul_f32_e32 v124, v45, v88
	v_mul_f32_e32 v134, v47, v80
	v_pk_mov_b32 v[140:141], v[84:85], v[82:83] op_sel:[1,0]
; #define LAS __attribute__((address_space(3)))
; __device__ __forceinline__ void ph_s5_out(unsigned char* lds_, const bf16_t* Z, const bf16_t* TZB, const bf16_t* CQ, const float2* LP, const float* SLOC, const float* lamT, bf16_t* YG, int nrct, int u0, int ustep) { PH_IDS;
;     ...
;         {
; #pragma unroll
;             for (int d = 0; d < 2; ++d)
; #pragma unroll 1
;             for (int ph = 0; ph < 2; ++ph) {
;                 asm volatile("" ::: "memory");
;                 const bf16x8 cqr = *(const LAS bf16x8*)(sm + O_SL + 9216 + (c16 * 256 + 32 * (4 * d + ph) + 8 * kq) * 2), cqi = *(const LAS bf16x8*)(sm + O_SL + 9216 + (c16 * 256 + 32 * (4 * d + 2 + ph) + 8 * kq) * 2);
;                 const bf16x8 xre = *(const LAS bf16x8*)(xb + (4 * d + ph) * 64), xim = *(const LAS bf16x8*)(xb + (4 * d + 2 + ph) * 64);
;                 float yr[8], yi[8], lr[8], li[8];
; #pragma unroll
;                 for (int j = 0; j < 8; ++j) {
;                     const int p_ = 32 * ph + 8 * kq + j;
;                     const f32x2v l1 = *(const LAS f32x2v*)(sm + O_SL + (d * 64 + p_) * 8), ls = *(const LAS f32x2v*)(sm + O_SL + (128 + (wid * 2 + d) * 64 + p_) * 8);
;                     const float xr = __uint_as_float((unsigned)(unsigned short)xre[j] << 16), xi = __uint_as_float((unsigned)(unsigned short)xim[j] << 16);
;                     yr[j] = ls.x * xr - ls.y * xi; yi[j] = ls.x * xi + ls.y * xr; lr[j] = l1.x; li[j] = l1.y;
;                 }
; #pragma unroll
;                 for (int s8 = 0; s8 < 8; ++s8) {
;                     const int i = d == 0 ? s8 : 7 - s8;
;                     const bf16x8 bre = __builtin_bit_cast(bf16x8, pack8((f32x4){yr[0], yr[1], yr[2], yr[3]}, (f32x4){yr[4], yr[5], yr[6], yr[7]}));
;                     const bf16x8 bim = __builtin_bit_cast(bf16x8, pack8((f32x4){yi[0], yi[1], yi[2], yi[3]}, (f32x4){yi[4], yi[5], yi[6], yi[7]}));
;                     acc8[i] = __builtin_amdgcn_mfma_f32_16x16x32_bf16(cqr, bre, acc8[i], 0, 0, 0);
;                     acc8[i] = __builtin_amdgcn_mfma_f32_16x16x32_bf16(cqi, bim, acc8[i], 0, 0, 0);
;                     if (s8 < 7) {
; #pragma unroll
;                         for (int j = 0; j < 8; ++j) { const float a = yr[j], c = yi[j]; yr[j] = lr[j] * a - li[j] * c; yi[j] = lr[j] * c + li[j] * a; }
;                     }
;                 }
;             }
	v_cvt_pk_bf16_f32 v69, v80, v82
	v_mul_f32_e32 v74, v49, v82
	v_pk_fma_f32 v[80:81], v[50:51], v[98:99], v[100:101] op_sel_hi:[1,1,0] neg_lo:[0,0,1] neg_hi:[0,0,1]
	v_pk_fma_f32 v[82:83], v[50:51], v[96:97], v[102:103] op_sel_hi:[1,1,0]
	v_pk_fma_f32 v[84:85], v[52:53], v[106:107], v[72:73] op_sel_hi:[1,1,0] neg_lo:[0,0,1] neg_hi:[0,0,1]
	v_pk_fma_f32 v[86:87], v[52:53], v[104:105], v[108:109] op_sel_hi:[1,1,0]
	v_pk_fma_f32 v[88:89], v[42:43], v[112:113], v[116:117] op_sel_hi:[1,1,0]
	v_pk_fma_f32 v[98:99], v[44:45], v[118:119], v[126:127] op_sel_hi:[1,1,0]
	v_pk_fma_f32 v[102:103], v[46:47], v[128:129], v[136:137] op_sel_hi:[1,1,0]
	v_pk_fma_f32 v[76:77], v[48:49], v[138:139], v[76:77] op_sel_hi:[1,1,0]
	v_pk_mul_f32 v[104:105], v[54:55], v[70:71] op_sel_hi:[1,0]
	v_pk_mul_f32 v[106:107], v[56:57], v[94:95] op_sel_hi:[1,0]
	v_pk_fma_f32 v[78:79], v[42:43], v[114:115], v[78:79] op_sel_hi:[1,1,0] neg_lo:[0,0,1] neg_hi:[0,0,1]
	v_pk_fma_f32 v[96:97], v[44:45], v[122:123], v[124:125] op_sel_hi:[1,1,0] neg_lo:[0,0,1] neg_hi:[0,0,1]
	v_pk_fma_f32 v[100:101], v[46:47], v[132:133], v[134:135] op_sel_hi:[1,1,0] neg_lo:[0,0,1] neg_hi:[0,0,1]
	v_mfma_f32_16x16x32_bf16 v[10:13], v[38:41], v[62:65], v[10:13]
	v_pk_fma_f32 v[74:75], v[48:49], v[140:141], v[74:75] op_sel_hi:[1,1,0] neg_lo:[0,0,1] neg_hi:[0,0,1]
	v_cvt_pk_bf16_f32 v62, v90, v92
	v_cvt_pk_bf16_f32 v63, v80, v84
	v_cvt_pk_bf16_f32 v64, v78, v96
	v_mfma_f32_16x16x32_bf16 v[10:13], v[34:37], v[66:69], v[10:13]
	v_cvt_pk_bf16_f32 v65, v100, v74
	v_cvt_pk_bf16_f32 v70, v70, v94
	v_cvt_pk_bf16_f32 v71, v82, v86
	v_cvt_pk_bf16_f32 v72, v88, v98
	v_cvt_pk_bf16_f32 v73, v102, v76
	v_fma_f32 v94, v55, v90, v104
	v_fma_f32 v95, v54, v90, v105
	v_pk_fma_f32 v[90:91], v[54:55], v[90:91], v[104:105] op_sel:[1,0,0] op_sel_hi:[0,0,1] neg_lo:[0,0,1] neg_hi:[0,0,1]
	v_pk_fma_f32 v[104:105], v[56:57], v[92:93], v[106:107] op_sel:[1,0,0] op_sel_hi:[0,0,1]
	v_pk_fma_f32 v[92:93], v[56:57], v[92:93], v[106:107] op_sel:[1,0,0] op_sel_hi:[0,0,1] neg_lo:[0,0,1] neg_hi:[0,0,1]
	v_pk_mul_f32 v[82:83], v[50:51], v[82:83] op_sel_hi:[1,0]
	v_pk_mul_f32 v[86:87], v[52:53], v[86:87] op_sel_hi:[1,0]
	v_pk_mul_f32 v[88:89], v[42:43], v[88:89] op_sel_hi:[1,0]
	v_pk_mul_f32 v[98:99], v[44:45], v[98:99] op_sel_hi:[1,0]
	v_pk_mul_f32 v[102:103], v[46:47], v[102:103] op_sel_hi:[1,0]
	v_pk_mul_f32 v[76:77], v[48:49], v[76:77] op_sel_hi:[1,0]
	v_mfma_f32_16x16x32_bf16 v[2:5], v[38:41], v[62:65], v[2:5]
	v_mov_b32_e32 v64, v94
	v_mov_b32_e32 v65, v91
	v_pk_mov_b32 v[106:107], v[90:91], v[94:95] op_sel:[1,0]
	v_mul_f32_e32 v90, v55, v94
	v_mul_f32_e32 v108, v55, v91
	v_mov_b32_e32 v110, v104
	v_mov_b32_e32 v111, v93
	v_pk_mov_b32 v[112:113], v[92:93], v[104:105] op_sel:[1,0]
	v_mul_f32_e32 v92, v57, v104
	v_mul_f32_e32 v114, v57, v93
	v_pk_fma_f32 v[116:117], v[50:51], v[80:81], v[82:83] op_sel:[1,0,0] op_sel_hi:[0,0,1]
	v_pk_fma_f32 v[80:81], v[50:51], v[80:81], v[82:83] op_sel:[1,0,0] op_sel_hi:[0,0,1] neg_lo:[0,0,1] neg_hi:[0,0,1]
	v_pk_fma_f32 v[82:83], v[52:53], v[84:85], v[86:87] op_sel:[1,0,0] op_sel_hi:[0,0,1]
	v_pk_fma_f32 v[84:85], v[52:53], v[84:85], v[86:87] op_sel:[1,0,0] op_sel_hi:[0,0,1] neg_lo:[0,0,1] neg_hi:[0,0,1]
	v_pk_fma_f32 v[86:87], v[42:43], v[78:79], v[88:89] op_sel:[1,0,0] op_sel_hi:[0,0,1]
	v_pk_fma_f32 v[78:79], v[42:43], v[78:79], v[88:89] op_sel:[1,0,0] op_sel_hi:[0,0,1] neg_lo:[0,0,1] neg_hi:[0,0,1]
	v_pk_fma_f32 v[88:89], v[44:45], v[96:97], v[98:99] op_sel:[1,0,0] op_sel_hi:[0,0,1]
	v_pk_fma_f32 v[96:97], v[44:45], v[96:97], v[98:99] op_sel:[1,0,0] op_sel_hi:[0,0,1] neg_lo:[0,0,1] neg_hi:[0,0,1]
	v_pk_fma_f32 v[98:99], v[46:47], v[100:101], v[102:103] op_sel:[1,0,0] op_sel_hi:[0,0,1]
	v_pk_fma_f32 v[100:101], v[46:47], v[100:101], v[102:103] op_sel:[1,0,0] op_sel_hi:[0,0,1] neg_lo:[0,0,1] neg_hi:[0,0,1]
	v_pk_fma_f32 v[102:103], v[48:49], v[74:75], v[76:77] op_sel:[1,0,0] op_sel_hi:[0,0,1]
	v_pk_fma_f32 v[118:119], v[48:49], v[74:75], v[76:77] op_sel:[1,0,0] op_sel_hi:[0,0,1] neg_lo:[0,0,1] neg_hi:[0,0,1]
	v_cvt_pk_bf16_f32 v62, v91, v93
	v_pk_fma_f32 v[90:91], v[54:55], v[106:107], v[90:91] op_sel_hi:[1,1,0] neg_lo:[0,0,1] neg_hi:[0,0,1]
	v_pk_fma_f32 v[106:107], v[54:55], v[64:65], v[108:109] op_sel_hi:[1,1,0]
	v_pk_fma_f32 v[92:93], v[56:57], v[112:113], v[92:93] op_sel_hi:[1,1,0] neg_lo:[0,0,1] neg_hi:[0,0,1]
	v_pk_fma_f32 v[108:109], v[56:57], v[110:111], v[114:115] op_sel_hi:[1,1,0]
	v_mov_b32_e32 v110, v116
	v_mov_b32_e32 v111, v81
	v_pk_mov_b32 v[112:113], v[80:81], v[116:117] op_sel:[1,0]
	v_mul_f32_e32 v80, v51, v116
	v_mul_f32_e32 v114, v51, v81
	v_mov_b32_e32 v120, v82
	v_mov_b32_e32 v121, v85
	v_cvt_pk_bf16_f32 v63, v81, v85
	v_mul_f32_e32 v124, v53, v85
	v_mov_b32_e32 v126, v86
	v_mov_b32_e32 v127, v79
	v_pk_mov_b32 v[128:129], v[78:79], v[86:87] op_sel:[1,0]
	v_mul_f32_e32 v78, v43, v86
	v_mul_f32_e32 v132, v43, v79
	v_mov_b32_e32 v134, v88
	v_mov_b32_e32 v135, v97
	v_cvt_pk_bf16_f32 v64, v79, v97
	v_mul_f32_e32 v138, v45, v97
	v_mov_b32_e32 v140, v98
	v_mov_b32_e32 v141, v101
	v_mul_f32_e32 v144, v47, v101
	v_mov_b32_e32 v146, v102
	v_mov_b32_e32 v147, v119
	v_cvt_pk_bf16_f32 v65, v101, v119
	v_cvt_pk_bf16_f32 v74, v94, v104
	v_cvt_pk_bf16_f32 v75, v116, v82
	v_cvt_pk_bf16_f32 v76, v86, v88
	v_mul_f32_e32 v86, v49, v119
	v_pk_mov_b32 v[122:123], v[84:85], v[82:83] op_sel:[1,0]
	v_mul_f32_e32 v84, v53, v82
	v_pk_mov_b32 v[136:137], v[96:97], v[88:89] op_sel:[1,0]
	v_mul_f32_e32 v96, v45, v88
	v_pk_mov_b32 v[142:143], v[100:101], v[98:99] op_sel:[1,0]
	v_mul_f32_e32 v100, v47, v98
	v_pk_mov_b32 v[148:149], v[118:119], v[102:103] op_sel:[1,0]
	v_cvt_pk_bf16_f32 v77, v98, v102
; #define LAS __attribute__((address_space(3)))
; __device__ __forceinline__ void ph_s5_out(unsigned char* lds_, const bf16_t* Z, const bf16_t* TZB, const bf16_t* CQ, const float2* LP, const float* SLOC, const float* lamT, bf16_t* YG, int nrct, int u0, int ustep) { PH_IDS;
;     ...
;         {
; #pragma unroll
;             for (int d = 0; d < 2; ++d)
; #pragma unroll 1
;             for (int ph = 0; ph < 2; ++ph) {
;                 asm volatile("" ::: "memory");
;                 const bf16x8 cqr = *(const LAS bf16x8*)(sm + O_SL + 9216 + (c16 * 256 + 32 * (4 * d + ph) + 8 * kq) * 2), cqi = *(const LAS bf16x8*)(sm + O_SL + 9216 + (c16 * 256 + 32 * (4 * d + 2 + ph) + 8 * kq) * 2);
;                 const bf16x8 xre = *(const LAS bf16x8*)(xb + (4 * d + ph) * 64), xim = *(const LAS bf16x8*)(xb + (4 * d + 2 + ph) * 64);
;                 float yr[8], yi[8], lr[8], li[8];
; #pragma unroll
;                 for (int j = 0; j < 8; ++j) {
;                     const int p_ = 32 * ph + 8 * kq + j;
;                     const f32x2v l1 = *(const LAS f32x2v*)(sm + O_SL + (d * 64 + p_) * 8), ls = *(const LAS f32x2v*)(sm + O_SL + (128 + (wid * 2 + d) * 64 + p_) * 8);
;                     const float xr = __uint_as_float((unsigned)(unsigned short)xre[j] << 16), xi = __uint_as_float((unsigned)(unsigned short)xim[j] << 16);
;                     yr[j] = ls.x * xr - ls.y * xi; yi[j] = ls.x * xi + ls.y * xr; lr[j] = l1.x; li[j] = l1.y;
;                 }
; #pragma unroll
;                 for (int s8 = 0; s8 < 8; ++s8) {
;                     const int i = d == 0 ? s8 : 7 - s8;
;                     const bf16x8 bre = __builtin_bit_cast(bf16x8, pack8((f32x4){yr[0], yr[1], yr[2], yr[3]}, (f32x4){yr[4], yr[5], yr[6], yr[7]}));
;                     const bf16x8 bim = __builtin_bit_cast(bf16x8, pack8((f32x4){yi[0], yi[1], yi[2], yi[3]}, (f32x4){yi[4], yi[5], yi[6], yi[7]}));
;                     acc8[i] = __builtin_amdgcn_mfma_f32_16x16x32_bf16(cqr, bre, acc8[i], 0, 0, 0);
;                     acc8[i] = __builtin_amdgcn_mfma_f32_16x16x32_bf16(cqi, bim, acc8[i], 0, 0, 0);
;                     if (s8 < 7) {
; #pragma unroll
;                         for (int j = 0; j < 8; ++j) { const float a = yr[j], c = yi[j]; yr[j] = lr[j] * a - li[j] * c; yi[j] = lr[j] * c + li[j] * a; }
;                     }
;                 }
;             }
	v_mul_f32_e32 v82, v49, v102
	v_pk_fma_f32 v[80:81], v[50:51], v[112:113], v[80:81] op_sel_hi:[1,1,0] neg_lo:[0,0,1] neg_hi:[0,0,1]
	v_pk_fma_f32 v[88:89], v[50:51], v[110:111], v[114:115] op_sel_hi:[1,1,0]
	v_pk_fma_f32 v[94:95], v[52:53], v[120:121], v[124:125] op_sel_hi:[1,1,0]
	v_pk_fma_f32 v[98:99], v[42:43], v[126:127], v[132:133] op_sel_hi:[1,1,0]
	v_pk_fma_f32 v[102:103], v[44:45], v[134:135], v[138:139] op_sel_hi:[1,1,0]
	v_pk_fma_f32 v[104:105], v[46:47], v[140:141], v[144:145] op_sel_hi:[1,1,0]
	v_pk_fma_f32 v[86:87], v[48:49], v[146:147], v[86:87] op_sel_hi:[1,1,0]
	v_pk_mul_f32 v[110:111], v[54:55], v[106:107] op_sel_hi:[1,0]
	v_pk_mul_f32 v[112:113], v[56:57], v[108:109] op_sel_hi:[1,0]
	v_pk_fma_f32 v[84:85], v[52:53], v[122:123], v[84:85] op_sel_hi:[1,1,0] neg_lo:[0,0,1] neg_hi:[0,0,1]
	v_pk_fma_f32 v[78:79], v[42:43], v[128:129], v[78:79] op_sel_hi:[1,1,0] neg_lo:[0,0,1] neg_hi:[0,0,1]
	v_pk_fma_f32 v[96:97], v[44:45], v[136:137], v[96:97] op_sel_hi:[1,1,0] neg_lo:[0,0,1] neg_hi:[0,0,1]
	v_pk_fma_f32 v[100:101], v[46:47], v[142:143], v[100:101] op_sel_hi:[1,1,0] neg_lo:[0,0,1] neg_hi:[0,0,1]
	v_mfma_f32_16x16x32_bf16 v[18:21], v[38:41], v[62:65], v[18:21]
	v_pk_fma_f32 v[82:83], v[48:49], v[148:149], v[82:83] op_sel_hi:[1,1,0] neg_lo:[0,0,1] neg_hi:[0,0,1]
	v_cvt_pk_bf16_f32 v62, v90, v92
	v_cvt_pk_bf16_f32 v63, v80, v84
	v_cvt_pk_bf16_f32 v64, v78, v96
	v_mfma_f32_16x16x32_bf16 v[2:5], v[34:37], v[70:73], v[2:5]
	v_cvt_pk_bf16_f32 v65, v100, v82
	v_cvt_pk_bf16_f32 v66, v106, v108
	v_cvt_pk_bf16_f32 v67, v88, v94
	v_cvt_pk_bf16_f32 v68, v98, v102
	v_cvt_pk_bf16_f32 v69, v104, v86
	v_fma_f32 v106, v55, v90, v110
	v_fma_f32 v107, v54, v90, v111
	v_pk_fma_f32 v[90:91], v[54:55], v[90:91], v[110:111] op_sel:[1,0,0] op_sel_hi:[0,0,1] neg_lo:[0,0,1] neg_hi:[0,0,1]
	v_pk_fma_f32 v[108:109], v[56:57], v[92:93], v[112:113] op_sel:[1,0,0] op_sel_hi:[0,0,1]
	v_pk_fma_f32 v[92:93], v[56:57], v[92:93], v[112:113] op_sel:[1,0,0] op_sel_hi:[0,0,1] neg_lo:[0,0,1] neg_hi:[0,0,1]
	v_pk_mul_f32 v[88:89], v[50:51], v[88:89] op_sel_hi:[1,0]
	v_pk_mul_f32 v[94:95], v[52:53], v[94:95] op_sel_hi:[1,0]
	v_pk_mul_f32 v[98:99], v[42:43], v[98:99] op_sel_hi:[1,0]
	v_pk_mul_f32 v[70:71], v[44:45], v[102:103] op_sel_hi:[1,0]
	v_pk_mul_f32 v[72:73], v[46:47], v[104:105] op_sel_hi:[1,0]
	v_pk_mul_f32 v[86:87], v[48:49], v[86:87] op_sel_hi:[1,0]
	v_mfma_f32_16x16x32_bf16 v[6:9], v[38:41], v[62:65], v[6:9]
	v_mov_b32_e32 v64, v106
	v_mov_b32_e32 v65, v91
	v_pk_mov_b32 v[102:103], v[90:91], v[106:107] op_sel:[1,0]
	v_mul_f32_e32 v90, v55, v106
	v_mul_f32_e32 v104, v55, v91
	v_mov_b32_e32 v110, v108
	v_mov_b32_e32 v111, v93
	v_pk_mov_b32 v[112:113], v[92:93], v[108:109] op_sel:[1,0]
	v_mul_f32_e32 v92, v57, v108
	v_mul_f32_e32 v114, v57, v93
	v_pk_fma_f32 v[116:117], v[50:51], v[80:81], v[88:89] op_sel:[1,0,0] op_sel_hi:[0,0,1]
	v_pk_fma_f32 v[80:81], v[50:51], v[80:81], v[88:89] op_sel:[1,0,0] op_sel_hi:[0,0,1] neg_lo:[0,0,1] neg_hi:[0,0,1]
	v_pk_fma_f32 v[88:89], v[52:53], v[84:85], v[94:95] op_sel:[1,0,0] op_sel_hi:[0,0,1]
	v_pk_fma_f32 v[84:85], v[52:53], v[84:85], v[94:95] op_sel:[1,0,0] op_sel_hi:[0,0,1] neg_lo:[0,0,1] neg_hi:[0,0,1]
	v_pk_fma_f32 v[94:95], v[42:43], v[78:79], v[98:99] op_sel:[1,0,0] op_sel_hi:[0,0,1]
	v_pk_fma_f32 v[78:79], v[42:43], v[78:79], v[98:99] op_sel:[1,0,0] op_sel_hi:[0,0,1] neg_lo:[0,0,1] neg_hi:[0,0,1]
	v_pk_fma_f32 v[98:99], v[44:45], v[96:97], v[70:71] op_sel:[1,0,0] op_sel_hi:[0,0,1]
	v_pk_fma_f32 v[70:71], v[44:45], v[96:97], v[70:71] op_sel:[1,0,0] op_sel_hi:[0,0,1] neg_lo:[0,0,1] neg_hi:[0,0,1]
	v_pk_fma_f32 v[96:97], v[46:47], v[100:101], v[72:73] op_sel:[1,0,0] op_sel_hi:[0,0,1]
	v_pk_fma_f32 v[72:73], v[46:47], v[100:101], v[72:73] op_sel:[1,0,0] op_sel_hi:[0,0,1] neg_lo:[0,0,1] neg_hi:[0,0,1]
	v_pk_fma_f32 v[100:101], v[48:49], v[82:83], v[86:87] op_sel:[1,0,0] op_sel_hi:[0,0,1]
	v_pk_fma_f32 v[82:83], v[48:49], v[82:83], v[86:87] op_sel:[1,0,0] op_sel_hi:[0,0,1] neg_lo:[0,0,1] neg_hi:[0,0,1]
	v_cvt_pk_bf16_f32 v62, v91, v93
	v_pk_fma_f32 v[86:87], v[54:55], v[102:103], v[90:91] op_sel_hi:[1,1,0] neg_lo:[0,0,1] neg_hi:[0,0,1]
	v_pk_fma_f32 v[90:91], v[54:55], v[64:65], v[104:105] op_sel_hi:[1,1,0]
	v_pk_fma_f32 v[92:93], v[56:57], v[112:113], v[92:93] op_sel_hi:[1,1,0] neg_lo:[0,0,1] neg_hi:[0,0,1]
	v_pk_fma_f32 v[102:103], v[56:57], v[110:111], v[114:115] op_sel_hi:[1,1,0]
	v_mov_b32_e32 v104, v116
	v_mov_b32_e32 v105, v81
	v_pk_mov_b32 v[110:111], v[80:81], v[116:117] op_sel:[1,0]
	v_mul_f32_e32 v80, v51, v116
	v_mul_f32_e32 v112, v51, v81
	v_mov_b32_e32 v114, v88
	v_mov_b32_e32 v115, v85
	v_pk_mov_b32 v[118:119], v[84:85], v[88:89] op_sel:[1,0]
	v_cvt_pk_bf16_f32 v63, v81, v85
	v_mul_f32_e32 v84, v53, v88
	v_mul_f32_e32 v120, v53, v85
	v_mov_b32_e32 v122, v94
	v_mov_b32_e32 v123, v79
	v_mul_f32_e32 v126, v43, v79
	v_mov_b32_e32 v128, v98
	v_mov_b32_e32 v129, v71
	v_pk_mov_b32 v[132:133], v[70:71], v[98:99] op_sel:[1,0]
	v_cvt_pk_bf16_f32 v64, v79, v71
	v_mul_f32_e32 v136, v45, v71
	v_mov_b32_e32 v138, v96
	v_mov_b32_e32 v139, v73
	v_mul_f32_e32 v144, v47, v73
	v_mov_b32_e32 v146, v100
	v_mov_b32_e32 v147, v83
	v_cvt_pk_bf16_f32 v65, v73, v83
	v_cvt_pk_bf16_f32 v70, v106, v108
	v_cvt_pk_bf16_f32 v71, v116, v88
	v_mul_f32_e32 v88, v49, v83
	v_pk_mov_b32 v[124:125], v[78:79], v[94:95] op_sel:[1,0]
	v_mul_f32_e32 v78, v43, v94
	v_mul_f32_e32 v134, v45, v98
	v_pk_mov_b32 v[140:141], v[72:73], v[96:97] op_sel:[1,0]
	v_mul_f32_e32 v142, v47, v96
	v_pk_mov_b32 v[148:149], v[82:83], v[100:101] op_sel:[1,0]
	v_cvt_pk_bf16_f32 v72, v94, v98
	v_cvt_pk_bf16_f32 v73, v96, v100
	v_mul_f32_e32 v82, v49, v100
; #define LAS __attribute__((address_space(3)))
; __device__ __forceinline__ void ph_s5_out(unsigned char* lds_, const bf16_t* Z, const bf16_t* TZB, const bf16_t* CQ, const float2* LP, const float* SLOC, const float* lamT, bf16_t* YG, int nrct, int u0, int ustep) { PH_IDS;
;     ...
;         {
; #pragma unroll
;             for (int d = 0; d < 2; ++d)
; #pragma unroll 1
;             for (int ph = 0; ph < 2; ++ph) {
;                 asm volatile("" ::: "memory");
;                 const bf16x8 cqr = *(const LAS bf16x8*)(sm + O_SL + 9216 + (c16 * 256 + 32 * (4 * d + ph) + 8 * kq) * 2), cqi = *(const LAS bf16x8*)(sm + O_SL + 9216 + (c16 * 256 + 32 * (4 * d + 2 + ph) + 8 * kq) * 2);
;                 const bf16x8 xre = *(const LAS bf16x8*)(xb + (4 * d + ph) * 64), xim = *(const LAS bf16x8*)(xb + (4 * d + 2 + ph) * 64);
;                 float yr[8], yi[8], lr[8], li[8];
; #pragma unroll
;                 for (int j = 0; j < 8; ++j) {
;                     const int p_ = 32 * ph + 8 * kq + j;
;                     const f32x2v l1 = *(const LAS f32x2v*)(sm + O_SL + (d * 64 + p_) * 8), ls = *(const LAS f32x2v*)(sm + O_SL + (128 + (wid * 2 + d) * 64 + p_) * 8);
;                     const float xr = __uint_as_float((unsigned)(unsigned short)xre[j] << 16), xi = __uint_as_float((unsigned)(unsigned short)xim[j] << 16);
;                     yr[j] = ls.x * xr - ls.y * xi; yi[j] = ls.x * xi + ls.y * xr; lr[j] = l1.x; li[j] = l1.y;
;                 }
; #pragma unroll
;                 for (int s8 = 0; s8 < 8; ++s8) {
;                     const int i = d == 0 ? s8 : 7 - s8;
;                     const bf16x8 bre = __builtin_bit_cast(bf16x8, pack8((f32x4){yr[0], yr[1], yr[2], yr[3]}, (f32x4){yr[4], yr[5], yr[6], yr[7]}));
;                     const bf16x8 bim = __builtin_bit_cast(bf16x8, pack8((f32x4){yi[0], yi[1], yi[2], yi[3]}, (f32x4){yi[4], yi[5], yi[6], yi[7]}));
;                     acc8[i] = __builtin_amdgcn_mfma_f32_16x16x32_bf16(cqr, bre, acc8[i], 0, 0, 0);
;                     acc8[i] = __builtin_amdgcn_mfma_f32_16x16x32_bf16(cqi, bim, acc8[i], 0, 0, 0);
;                     if (s8 < 7) {
; #pragma unroll
;                         for (int j = 0; j < 8; ++j) { const float a = yr[j], c = yi[j]; yr[j] = lr[j] * a - li[j] * c; yi[j] = lr[j] * c + li[j] * a; }
;                     }
;                 }
;             }
	v_pk_fma_f32 v[80:81], v[50:51], v[110:111], v[80:81] op_sel_hi:[1,1,0] neg_lo:[0,0,1] neg_hi:[0,0,1]
	v_pk_fma_f32 v[94:95], v[50:51], v[104:105], v[112:113] op_sel_hi:[1,1,0]
	v_pk_fma_f32 v[96:97], v[52:53], v[114:115], v[120:121] op_sel_hi:[1,1,0]
	v_pk_fma_f32 v[98:99], v[42:43], v[122:123], v[126:127] op_sel_hi:[1,1,0]
	v_pk_fma_f32 v[104:105], v[44:45], v[128:129], v[136:137] op_sel_hi:[1,1,0]
	v_pk_fma_f32 v[108:109], v[46:47], v[138:139], v[144:145] op_sel_hi:[1,1,0]
	v_pk_fma_f32 v[88:89], v[48:49], v[146:147], v[88:89] op_sel_hi:[1,1,0]
	v_pk_mul_f32 v[110:111], v[54:55], v[90:91] op_sel_hi:[1,0]
	v_pk_mul_f32 v[112:113], v[56:57], v[102:103] op_sel_hi:[1,0]
	v_mfma_f32_16x16x32_bf16 v[18:21], v[34:37], v[74:77], v[18:21]
	v_pk_fma_f32 v[84:85], v[52:53], v[118:119], v[84:85] op_sel_hi:[1,1,0] neg_lo:[0,0,1] neg_hi:[0,0,1]
	v_pk_fma_f32 v[78:79], v[42:43], v[124:125], v[78:79] op_sel_hi:[1,1,0] neg_lo:[0,0,1] neg_hi:[0,0,1]
	v_pk_fma_f32 v[100:101], v[44:45], v[132:133], v[134:135] op_sel_hi:[1,1,0] neg_lo:[0,0,1] neg_hi:[0,0,1]
	v_pk_fma_f32 v[106:107], v[46:47], v[140:141], v[142:143] op_sel_hi:[1,1,0] neg_lo:[0,0,1] neg_hi:[0,0,1]
	v_mfma_f32_16x16x32_bf16 v[22:25], v[38:41], v[62:65], v[22:25]
	v_pk_fma_f32 v[82:83], v[48:49], v[148:149], v[82:83] op_sel_hi:[1,1,0] neg_lo:[0,0,1] neg_hi:[0,0,1]
	v_cvt_pk_bf16_f32 v62, v86, v92
	v_cvt_pk_bf16_f32 v63, v80, v84
	v_cvt_pk_bf16_f32 v64, v78, v100
	v_mfma_f32_16x16x32_bf16 v[6:9], v[34:37], v[66:69], v[6:9]
	v_cvt_pk_bf16_f32 v65, v106, v82
	v_cvt_pk_bf16_f32 v74, v90, v102
	v_cvt_pk_bf16_f32 v75, v94, v96
	v_cvt_pk_bf16_f32 v76, v98, v104
	v_cvt_pk_bf16_f32 v77, v108, v88
	v_pk_mul_f32 v[88:89], v[48:49], v[88:89] op_sel_hi:[1,0]
	v_pk_fma_f32 v[90:91], v[54:55], v[86:87], v[110:111] op_sel:[1,0,0] op_sel_hi:[0,0,1]
	v_pk_fma_f32 v[86:87], v[54:55], v[86:87], v[110:111] op_sel:[1,0,0] op_sel_hi:[0,0,1] neg_lo:[0,0,1] neg_hi:[0,0,1]
	v_pk_fma_f32 v[102:103], v[56:57], v[92:93], v[112:113] op_sel:[1,0,0] op_sel_hi:[0,0,1]
	v_pk_fma_f32 v[92:93], v[56:57], v[92:93], v[112:113] op_sel:[1,0,0] op_sel_hi:[0,0,1] neg_lo:[0,0,1] neg_hi:[0,0,1]
	v_pk_mul_f32 v[94:95], v[50:51], v[94:95] op_sel_hi:[1,0]
	v_pk_mul_f32 v[96:97], v[52:53], v[96:97] op_sel_hi:[1,0]
	v_pk_mul_f32 v[66:67], v[42:43], v[98:99] op_sel_hi:[1,0]
	v_pk_mul_f32 v[68:69], v[44:45], v[104:105] op_sel_hi:[1,0]
	v_pk_mul_f32 v[98:99], v[46:47], v[108:109] op_sel_hi:[1,0]
	v_mfma_f32_16x16x32_bf16 v[14:17], v[38:41], v[62:65], v[14:17]
	v_fma_f32 v104, v49, v82, v88
	v_fma_f32 v105, v48, v82, v89
	v_pk_fma_f32 v[82:83], v[48:49], v[82:83], v[88:89] op_sel:[1,0,0] op_sel_hi:[0,0,1] neg_lo:[0,0,1] neg_hi:[0,0,1]
	v_mov_b32_e32 v65, v87
	v_pk_mov_b32 v[88:89], v[86:87], v[90:91] op_sel:[1,0]
	v_mov_b32_e32 v109, v93
	v_pk_mov_b32 v[110:111], v[92:93], v[102:103] op_sel:[1,0]
	v_cvt_pk_bf16_f32 v62, v87, v93
	v_pk_fma_f32 v[86:87], v[50:51], v[80:81], v[94:95] op_sel:[1,0,0] op_sel_hi:[0,0,1]
	v_pk_fma_f32 v[80:81], v[50:51], v[80:81], v[94:95] op_sel:[1,0,0] op_sel_hi:[0,0,1] neg_lo:[0,0,1] neg_hi:[0,0,1]
	v_pk_fma_f32 v[92:93], v[52:53], v[84:85], v[96:97] op_sel:[1,0,0] op_sel_hi:[0,0,1]
	v_pk_fma_f32 v[84:85], v[52:53], v[84:85], v[96:97] op_sel:[1,0,0] op_sel_hi:[0,0,1] neg_lo:[0,0,1] neg_hi:[0,0,1]
	v_pk_fma_f32 v[94:95], v[42:43], v[78:79], v[66:67] op_sel:[1,0,0] op_sel_hi:[0,0,1]
	v_pk_fma_f32 v[66:67], v[42:43], v[78:79], v[66:67] op_sel:[1,0,0] op_sel_hi:[0,0,1] neg_lo:[0,0,1] neg_hi:[0,0,1]
	v_pk_fma_f32 v[78:79], v[44:45], v[100:101], v[68:69] op_sel:[1,0,0] op_sel_hi:[0,0,1]
	v_pk_fma_f32 v[68:69], v[44:45], v[100:101], v[68:69] op_sel:[1,0,0] op_sel_hi:[0,0,1] neg_lo:[0,0,1] neg_hi:[0,0,1]
	v_pk_fma_f32 v[96:97], v[46:47], v[106:107], v[98:99] op_sel:[1,0,0] op_sel_hi:[0,0,1]
	v_pk_fma_f32 v[98:99], v[46:47], v[106:107], v[98:99] op_sel:[1,0,0] op_sel_hi:[0,0,1] neg_lo:[0,0,1] neg_hi:[0,0,1]
	v_mov_b32_e32 v64, v90
	v_cvt_pk_bf16_f32 v63, v81, v85
	v_mov_b32_e32 v120, v78
	v_mov_b32_e32 v121, v69
	v_pk_mov_b32 v[122:123], v[68:69], v[78:79] op_sel:[1,0]
	v_mov_b32_e32 v124, v96
	v_mov_b32_e32 v125, v99
	v_pk_mov_b32 v[126:127], v[98:99], v[96:97] op_sel:[1,0]
	v_mov_b32_e32 v108, v102
	v_mov_b32_e32 v100, v104
	v_mov_b32_e32 v101, v83
	v_pk_mul_f32 v[106:107], v[54:55], v[64:65]
	v_mov_b32_e32 v112, v86
	v_mov_b32_e32 v113, v81
	v_pk_mov_b32 v[114:115], v[80:81], v[86:87] op_sel:[1,0]
	v_mov_b32_e32 v116, v92
	v_mov_b32_e32 v117, v85
	v_pk_mov_b32 v[118:119], v[84:85], v[92:93] op_sel:[1,0]
	v_mov_b32_e32 v80, v94
	v_mov_b32_e32 v81, v67
	v_pk_mov_b32 v[84:85], v[66:67], v[94:95] op_sel:[1,0]
	v_cvt_pk_bf16_f32 v64, v67, v69
	v_pk_mov_b32 v[128:129], v[82:83], v[104:105] op_sel:[1,0]
	v_cvt_pk_bf16_f32 v65, v99, v83
	v_pk_mul_f32 v[82:83], v[44:45], v[120:121]
	v_mfma_f32_16x16x32_bf16 v[30:33], v[38:41], v[62:65], v[30:33]
	v_mul_f32_e64 v62, v46, v124
	v_mul_f32_e64 v63, v47, v125
	v_pk_mul_f32 v[44:45], v[44:45], v[122:123]
	v_pk_mul_f32 v[46:47], v[46:47], v[126:127]
	v_pk_mul_f32 v[108:109], v[56:57], v[108:109]
	v_cvt_pk_bf16_f32 v66, v90, v102
	v_cvt_pk_bf16_f32 v67, v86, v92
	v_cvt_pk_bf16_f32 v68, v94, v78
	v_pk_mul_f32 v[54:55], v[54:55], v[88:89]
	v_pk_mul_f32 v[56:57], v[56:57], v[110:111]
	v_mfma_f32_16x16x32_bf16 v[22:25], v[34:37], v[70:73], v[22:25]
	v_mul_f32_e64 v70, v48, v100
	v_mul_f32_e64 v71, v49, v101
	v_pk_mul_f32 v[72:73], v[50:51], v[112:113]
	v_pk_mul_f32 v[78:79], v[52:53], v[116:117]
	v_pk_mul_f32 v[80:81], v[42:43], v[80:81]
	v_pk_mul_f32 v[48:49], v[48:49], v[128:129]
	v_pk_mul_f32 v[50:51], v[50:51], v[114:115]
	v_pk_mul_f32 v[52:53], v[52:53], v[118:119]
	v_pk_mul_f32 v[42:43], v[42:43], v[84:85]
	v_sub_f32_e32 v44, v44, v45
	v_sub_f32_e32 v45, v46, v47
	v_cvt_pk_bf16_f32 v69, v96, v104
	v_sub_f32_e32 v54, v54, v55
	v_sub_f32_e32 v55, v56, v57
	v_sub_f32_e32 v48, v48, v49
	v_sub_f32_e32 v49, v50, v51
	v_sub_f32_e32 v50, v52, v53
	v_sub_f32_e32 v51, v42, v43
	v_cvt_pk_bf16_f32 v42, v54, v55
	v_cvt_pk_bf16_f32 v43, v49, v50
	v_cvt_pk_bf16_f32 v44, v51, v44
	v_cvt_pk_bf16_f32 v45, v45, v48
	v_add_f32_e32 v61, v106, v107
	v_mfma_f32_16x16x32_bf16 v[26:29], v[38:41], v[42:45], v[26:29]
	v_add_f32_e32 v40, v82, v83
	v_add_f32_e32 v41, v62, v63
	v_add_f32_e32 v86, v108, v109
	v_add_f32_e32 v56, v70, v71
	v_add_f32_e32 v57, v72, v73
	v_add_f32_e32 v64, v78, v79
	v_add_f32_e32 v65, v80, v81
	v_mfma_f32_16x16x32_bf16 v[14:17], v[34:37], v[74:77], v[14:17]
	v_cvt_pk_bf16_f32 v38, v61, v86
	v_cvt_pk_bf16_f32 v39, v57, v64
	v_cvt_pk_bf16_f32 v40, v65, v40
	v_mfma_f32_16x16x32_bf16 v[30:33], v[34:37], v[66:69], v[30:33]
	v_cvt_pk_bf16_f32 v41, v41, v56
	s_mov_b32 s9, 1
	s_and_b64 vcc, exec, s[6:7]
	v_mfma_f32_16x16x32_bf16 v[26:29], v[34:37], v[38:41], v[26:29]
	s_mov_b64 s[6:7], 0
	s_cbranch_vccnz .LBB0_2829
; __device__ __forceinline__ unsigned pk2(float lo, float hi) { unsigned r; asm volatile("v_cvt_pk_bf16_f32 %0, %1, %2" : "=v"(r) : "v"(lo), "v"(hi)); return r; }
; __device__ __forceinline__ float geluf_(float x) { return 0.5f * x * (1.f + tanhf(0.7978845608028654f * (x + 0.044715f * x * x * x))); }
; __device__ __forceinline__ void ph_s5_out(unsigned char* lds_, const bf16_t* Z, const bf16_t* TZB, const bf16_t* CQ, const float2* LP, const float* SLOC, const float* lamT, bf16_t* YG, int nrct, int u0, int ustep) { PH_IDS;
;     ...
; #pragma unroll
;         for (int i = 0; i < 8; ++i) { const int t = wid * 8 + i;
;             fa::u32x2 w; w.x = fa::pk2(geluf_(acc8[i][0]), geluf_(acc8[i][1])); w.y = fa::pk2(geluf_(acc8[i][2]), geluf_(acc8[i][3]));
;             *(fa::u32x2*)(YG + ((size_t)(rcbase + c16) * 64 + t) * ZW + C_S5 + g * 16 + 4 * kq) = w; }
	s_nop 5
	v_mul_f32_e32 v34, 0x3d372713, v26
	v_mul_f32_e32 v34, v26, v34
	v_fma_f32 v34, v26, v34, v26
	v_mul_f32_e32 v34, 0x3f4c422a, v34
	v_mul_f32_e32 v35, 0x4038aa3b, v34
	v_exp_f32_e32 v35, v35
	s_nop 0
	v_add_f32_e32 v35, 1.0, v35
	v_rcp_f32_e32 v35, v35
	s_nop 0
	v_fma_f32 v35, v35, -2.0, 1.0
	v_mul_f32_e32 v36, 0x3d372713, v27
	v_mul_f32_e32 v36, v27, v36
	v_fma_f32 v36, v27, v36, v27
	v_mul_f32_e32 v36, 0x3f4c422a, v36
	v_mul_f32_e32 v37, 0x4038aa3b, v36
	v_exp_f32_e32 v37, v37
	s_nop 0
	v_add_f32_e32 v37, 1.0, v37
	v_rcp_f32_e32 v37, v37
	s_nop 0
	v_fma_f32 v37, v37, -2.0, 1.0
	v_bfi_b32 v34, s73, v35, v34
	v_mul_f32_e32 v26, 0.5, v26
	v_add_f32_e32 v34, 1.0, v34
	v_mul_f32_e32 v26, v26, v34
	v_bfi_b32 v34, s73, v37, v36
	v_mul_f32_e32 v27, 0.5, v27
	v_add_f32_e32 v34, 1.0, v34
	v_mul_f32_e32 v27, v27, v34
	v_cvt_pk_bf16_f32 v34, v26, v27
	v_mul_f32_e32 v26, 0x3d372713, v28
	v_mul_f32_e32 v26, v28, v26
	v_fma_f32 v26, v28, v26, v28
	v_mul_f32_e32 v26, 0x3f4c422a, v26
	v_mul_f32_e32 v27, 0x4038aa3b, v26
	v_exp_f32_e32 v27, v27
	s_nop 0
	v_add_f32_e32 v27, 1.0, v27
	v_rcp_f32_e32 v27, v27
	s_nop 0
	v_fma_f32 v27, v27, -2.0, 1.0
	v_mul_f32_e32 v35, 0x3d372713, v29
	v_mul_f32_e32 v35, v29, v35
	v_fma_f32 v35, v29, v35, v29
	v_mul_f32_e32 v35, 0x3f4c422a, v35
	v_mul_f32_e32 v36, 0x4038aa3b, v35
	v_exp_f32_e32 v36, v36
	s_nop 0
	v_add_f32_e32 v36, 1.0, v36
	v_rcp_f32_e32 v36, v36
	s_nop 0
	v_fma_f32 v36, v36, -2.0, 1.0
	v_bfi_b32 v26, s73, v27, v26
	v_mul_f32_e32 v28, 0.5, v28
	v_add_f32_e32 v26, 1.0, v26
	v_bfi_b32 v35, s73, v36, v35
	v_mul_f32_e32 v28, v28, v26
	v_or_b32_e32 v26, s91, v168
	s_add_u32 s6, s62, 0x4c00000
	v_mul_f32_e32 v29, 0.5, v29
	v_add_f32_e32 v35, 1.0, v35
	v_lshlrev_b32_e32 v26, 6, v26
	v_mov_b32_e32 v27, v130
	s_addc_u32 s7, s63, 0
	v_mul_f32_e32 v29, v29, v35
	s_ashr_i32 s5, s4, 31
	v_cvt_pk_bf16_f32 v35, v28, v29
	v_lshl_add_u64 v[28:29], s[4:5], 0, v[26:27]
	v_lshlrev_b64 v[28:29], 12, v[28:29]
	v_lshl_add_u64 v[28:29], s[6:7], 0, v[28:29]
	s_lshl_b32 s54, s54, 1
	v_lshl_add_u64 v[28:29], v[28:29], 0, s[54:55]
	v_mov_b32_e32 v59, v130
	v_lshl_add_u64 v[28:29], v[28:29], 0, v[58:59]
	global_store_dwordx2 v[28:29], v[34:35], off offset:320
	v_mul_f32_e32 v28, 0x3d372713, v30
	v_mul_f32_e32 v28, v30, v28
	v_fma_f32 v28, v30, v28, v30
	v_mul_f32_e32 v28, 0x3f4c422a, v28
	v_mul_f32_e32 v29, 0x4038aa3b, v28
	v_exp_f32_e32 v29, v29
	s_nop 0
	v_add_f32_e32 v29, 1.0, v29
	v_rcp_f32_e32 v29, v29
	s_nop 0
	v_fma_f32 v29, v29, -2.0, 1.0
	v_mul_f32_e32 v34, 0x3d372713, v31
	v_mul_f32_e32 v34, v31, v34
	v_fma_f32 v34, v31, v34, v31
	v_mul_f32_e32 v34, 0x3f4c422a, v34
	v_mul_f32_e32 v35, 0x4038aa3b, v34
	v_exp_f32_e32 v35, v35
	s_nop 0
	v_add_f32_e32 v35, 1.0, v35
	v_rcp_f32_e32 v35, v35
	s_nop 0
	v_fma_f32 v35, v35, -2.0, 1.0
	v_bfi_b32 v28, s73, v29, v28
	v_mul_f32_e32 v30, 0.5, v30
	v_add_f32_e32 v28, 1.0, v28
	v_mul_f32_e32 v28, v30, v28
	v_bfi_b32 v30, s73, v35, v34
	v_mul_f32_e32 v29, 0.5, v31
	v_add_f32_e32 v30, 1.0, v30
	v_mul_f32_e32 v29, v29, v30
	v_cvt_pk_bf16_f32 v30, v28, v29
	v_mul_f32_e32 v28, 0x3d372713, v32
	v_mul_f32_e32 v28, v32, v28
	v_fma_f32 v28, v32, v28, v32
	v_mul_f32_e32 v28, 0x3f4c422a, v28
	v_mul_f32_e32 v29, 0x4038aa3b, v28
	v_exp_f32_e32 v29, v29
	s_nop 0
	v_add_f32_e32 v29, 1.0, v29
	v_rcp_f32_e32 v29, v29
	s_nop 0
	v_fma_f32 v29, v29, -2.0, 1.0
	v_mul_f32_e32 v31, 0x3d372713, v33
	v_mul_f32_e32 v31, v33, v31
	v_fma_f32 v31, v33, v31, v33
	v_mul_f32_e32 v31, 0x3f4c422a, v31
	v_mul_f32_e32 v34, 0x4038aa3b, v31
	v_exp_f32_e32 v34, v34
	s_nop 0
	v_add_f32_e32 v34, 1.0, v34
	v_rcp_f32_e32 v34, v34
	s_nop 0
	v_fma_f32 v34, v34, -2.0, 1.0
	v_bfi_b32 v28, s73, v29, v28
	v_bfi_b32 v31, s73, v34, v31
	v_mul_f32_e32 v32, 0.5, v32
	v_add_f32_e32 v28, 1.0, v28
	s_or_b32 s8, s4, 1
	v_mul_f32_e32 v29, 0.5, v33
	v_add_f32_e32 v31, 1.0, v31
	v_mul_f32_e32 v28, v32, v28
	v_mul_f32_e32 v29, v29, v31
	s_ashr_i32 s9, s8, 31
	v_cvt_pk_bf16_f32 v31, v28, v29
	v_lshl_add_u64 v[28:29], s[8:9], 0, v[26:27]
	v_lshlrev_b64 v[28:29], 12, v[28:29]
	v_lshlrev_b32_e32 v35, 2, v131
	v_lshl_add_u64 v[28:29], s[6:7], 0, v[28:29]
	v_lshl_add_u64 v[32:33], v[28:29], 0, s[54:55]
	v_lshlrev_b32_e32 v28, 1, v35
	v_mov_b32_e32 v29, v130
	v_lshl_add_u64 v[32:33], v[32:33], 0, v[28:29]
	v_mul_f32_e32 v29, 0x3d372713, v14
	v_mul_f32_e32 v29, v14, v29
	v_fma_f32 v29, v14, v29, v14
	v_mul_f32_e32 v29, 0x3f4c422a, v29
	global_store_dwordx2 v[32:33], v[30:31], off offset:320
	v_mul_f32_e32 v30, 0x4038aa3b, v29
	v_exp_f32_e32 v30, v30
	s_nop 0
	v_add_f32_e32 v30, 1.0, v30
	v_rcp_f32_e32 v30, v30
	s_nop 0
	v_fma_f32 v30, v30, -2.0, 1.0
	v_mul_f32_e32 v31, 0x3d372713, v15
	v_mul_f32_e32 v31, v15, v31
	v_fma_f32 v31, v15, v31, v15
	v_mul_f32_e32 v31, 0x3f4c422a, v31
	v_mul_f32_e32 v32, 0x4038aa3b, v31
	v_exp_f32_e32 v32, v32
	s_nop 0
	v_add_f32_e32 v32, 1.0, v32
	v_rcp_f32_e32 v32, v32
	s_nop 0
	v_fma_f32 v32, v32, -2.0, 1.0
	v_bfi_b32 v29, s73, v30, v29
	v_mul_f32_e32 v14, 0.5, v14
	v_add_f32_e32 v29, 1.0, v29
	v_mul_f32_e32 v14, v14, v29
	v_bfi_b32 v29, s73, v32, v31
	v_mul_f32_e32 v15, 0.5, v15
	v_add_f32_e32 v29, 1.0, v29
	v_mul_f32_e32 v15, v15, v29
	v_cvt_pk_bf16_f32 v14, v14, v15
	v_mul_f32_e32 v15, 0x3d372713, v16
	v_mul_f32_e32 v15, v16, v15
	v_fma_f32 v15, v16, v15, v16
	v_mul_f32_e32 v15, 0x3f4c422a, v15
	v_mul_f32_e32 v29, 0x4038aa3b, v15
	v_exp_f32_e32 v29, v29
	s_nop 0
	v_add_f32_e32 v29, 1.0, v29
	v_rcp_f32_e32 v29, v29
	s_nop 0
	v_fma_f32 v29, v29, -2.0, 1.0
	v_mul_f32_e32 v30, 0x3d372713, v17
	v_mul_f32_e32 v30, v17, v30
	v_fma_f32 v30, v17, v30, v17
	v_mul_f32_e32 v30, 0x3f4c422a, v30
	v_mul_f32_e32 v31, 0x4038aa3b, v30
; __device__ __forceinline__ unsigned pk2(float lo, float hi) { unsigned r; asm volatile("v_cvt_pk_bf16_f32 %0, %1, %2" : "=v"(r) : "v"(lo), "v"(hi)); return r; }
; __device__ __forceinline__ float geluf_(float x) { return 0.5f * x * (1.f + tanhf(0.7978845608028654f * (x + 0.044715f * x * x * x))); }
; __device__ __forceinline__ void ph_s5_out(unsigned char* lds_, const bf16_t* Z, const bf16_t* TZB, const bf16_t* CQ, const float2* LP, const float* SLOC, const float* lamT, bf16_t* YG, int nrct, int u0, int ustep) { PH_IDS;
;     ...
; #pragma unroll
;         for (int i = 0; i < 8; ++i) { const int t = wid * 8 + i;
;             fa::u32x2 w; w.x = fa::pk2(geluf_(acc8[i][0]), geluf_(acc8[i][1])); w.y = fa::pk2(geluf_(acc8[i][2]), geluf_(acc8[i][3]));
;             *(fa::u32x2*)(YG + ((size_t)(rcbase + c16) * 64 + t) * ZW + C_S5 + g * 16 + 4 * kq) = w; }
	v_exp_f32_e32 v31, v31
	s_nop 0
	v_add_f32_e32 v31, 1.0, v31
	v_rcp_f32_e32 v31, v31
	s_nop 0
	v_fma_f32 v31, v31, -2.0, 1.0
	v_bfi_b32 v15, s73, v29, v15
	v_mul_f32_e32 v16, 0.5, v16
	v_add_f32_e32 v15, 1.0, v15
	v_mul_f32_e32 v15, v16, v15
	v_mul_f32_e32 v16, 0.5, v17
	v_bfi_b32 v17, s73, v31, v30
	s_or_b32 s8, s4, 2
	v_add_f32_e32 v17, 1.0, v17
	v_mul_f32_e32 v16, v16, v17
	s_ashr_i32 s9, s8, 31
	v_cvt_pk_bf16_f32 v15, v15, v16
	v_lshl_add_u64 v[16:17], s[8:9], 0, v[26:27]
	v_lshlrev_b64 v[16:17], 12, v[16:17]
	v_lshl_add_u64 v[16:17], s[6:7], 0, v[16:17]
	v_lshl_add_u64 v[16:17], v[16:17], 0, s[54:55]
	v_mov_b32_e32 v29, v130
	v_lshl_add_u64 v[16:17], v[16:17], 0, v[28:29]
	global_store_dwordx2 v[16:17], v[14:15], off offset:320
	v_mul_f32_e32 v14, 0x3d372713, v22
	v_mul_f32_e32 v14, v22, v14
	v_fma_f32 v14, v22, v14, v22
	v_mul_f32_e32 v14, 0x3f4c422a, v14
	v_mul_f32_e32 v15, 0x4038aa3b, v14
	v_exp_f32_e32 v15, v15
	s_nop 0
	v_add_f32_e32 v15, 1.0, v15
	v_rcp_f32_e32 v15, v15
	s_nop 0
	v_fma_f32 v15, v15, -2.0, 1.0
	v_mul_f32_e32 v16, 0x3d372713, v23
	v_mul_f32_e32 v16, v23, v16
	v_fma_f32 v16, v23, v16, v23
	v_mul_f32_e32 v16, 0x3f4c422a, v16
	v_mul_f32_e32 v17, 0x4038aa3b, v16
	v_exp_f32_e32 v17, v17
	s_nop 0
	v_add_f32_e32 v17, 1.0, v17
	v_rcp_f32_e32 v17, v17
	s_nop 0
	v_fma_f32 v17, v17, -2.0, 1.0
	v_bfi_b32 v14, s73, v15, v14
	v_bfi_b32 v16, s73, v17, v16
	v_mul_f32_e32 v22, 0.5, v22
	v_add_f32_e32 v14, 1.0, v14
	v_mul_f32_e32 v15, 0.5, v23
	v_add_f32_e32 v16, 1.0, v16
	v_mul_f32_e32 v14, v22, v14
	v_mul_f32_e32 v15, v15, v16
	v_cvt_pk_bf16_f32 v14, v14, v15
	v_mul_f32_e32 v15, 0x3d372713, v24
	v_mul_f32_e32 v15, v24, v15
	v_fma_f32 v15, v24, v15, v24
	v_mul_f32_e32 v15, 0x3f4c422a, v15
	v_mul_f32_e32 v16, 0x4038aa3b, v15
	v_exp_f32_e32 v16, v16
	s_nop 0
	v_add_f32_e32 v16, 1.0, v16
	v_rcp_f32_e32 v16, v16
	s_nop 0
	v_fma_f32 v16, v16, -2.0, 1.0
	v_mul_f32_e32 v17, 0x3d372713, v25
	v_mul_f32_e32 v17, v25, v17
	v_fma_f32 v17, v25, v17, v25
	v_mul_f32_e32 v17, 0x3f4c422a, v17
	v_mul_f32_e32 v22, 0x4038aa3b, v17
	v_exp_f32_e32 v22, v22
	s_nop 0
	v_add_f32_e32 v22, 1.0, v22
	v_rcp_f32_e32 v22, v22
	s_nop 0
	v_fma_f32 v22, v22, -2.0, 1.0
	v_bfi_b32 v15, s73, v16, v15
	v_bfi_b32 v17, s73, v22, v17
	v_mul_f32_e32 v23, 0.5, v24
	v_add_f32_e32 v15, 1.0, v15
	s_or_b32 s8, s4, 3
	v_mul_f32_e32 v16, 0.5, v25
	v_add_f32_e32 v17, 1.0, v17
	v_mul_f32_e32 v15, v23, v15
	v_mul_f32_e32 v16, v16, v17
	s_ashr_i32 s9, s8, 31
	v_cvt_pk_bf16_f32 v15, v15, v16
	v_lshl_add_u64 v[16:17], s[8:9], 0, v[26:27]
	v_lshlrev_b64 v[16:17], 12, v[16:17]
	v_lshl_add_u64 v[16:17], s[6:7], 0, v[16:17]
	v_lshl_add_u64 v[16:17], v[16:17], 0, s[54:55]
	v_mov_b32_e32 v29, v130
	v_lshl_add_u64 v[16:17], v[16:17], 0, v[28:29]
	global_store_dwordx2 v[16:17], v[14:15], off offset:320
	v_mul_f32_e32 v14, 0x3d372713, v6
	v_mul_f32_e32 v14, v6, v14
	v_fma_f32 v14, v6, v14, v6
	v_mul_f32_e32 v14, 0x3f4c422a, v14
	v_mul_f32_e32 v15, 0x4038aa3b, v14
	v_exp_f32_e32 v15, v15
	s_nop 0
	v_add_f32_e32 v15, 1.0, v15
	v_rcp_f32_e32 v15, v15
	s_nop 0
	v_fma_f32 v15, v15, -2.0, 1.0
	v_mul_f32_e32 v16, 0x3d372713, v7
	v_mul_f32_e32 v16, v7, v16
	v_fma_f32 v16, v7, v16, v7
	v_mul_f32_e32 v16, 0x3f4c422a, v16
	v_mul_f32_e32 v17, 0x4038aa3b, v16
	v_exp_f32_e32 v17, v17
	s_nop 0
	v_add_f32_e32 v17, 1.0, v17
	v_rcp_f32_e32 v17, v17
	s_nop 0
	v_fma_f32 v17, v17, -2.0, 1.0
	v_bfi_b32 v14, s73, v15, v14
	v_mul_f32_e32 v6, 0.5, v6
	v_add_f32_e32 v14, 1.0, v14
	v_mul_f32_e32 v6, v6, v14
	v_bfi_b32 v14, s73, v17, v16
	v_mul_f32_e32 v7, 0.5, v7
	v_add_f32_e32 v14, 1.0, v14
	v_mul_f32_e32 v7, v7, v14
	v_cvt_pk_bf16_f32 v6, v6, v7
	v_mul_f32_e32 v7, 0x3d372713, v8
	v_mul_f32_e32 v7, v8, v7
	v_fma_f32 v7, v8, v7, v8
	v_mul_f32_e32 v7, 0x3f4c422a, v7
	v_mul_f32_e32 v14, 0x4038aa3b, v7
	v_exp_f32_e32 v14, v14
	s_nop 0
	v_add_f32_e32 v14, 1.0, v14
	v_rcp_f32_e32 v14, v14
	s_nop 0
	v_fma_f32 v14, v14, -2.0, 1.0
	v_mul_f32_e32 v15, 0x3d372713, v9
	v_mul_f32_e32 v15, v9, v15
	v_fma_f32 v15, v9, v15, v9
	v_mul_f32_e32 v15, 0x3f4c422a, v15
	v_mul_f32_e32 v16, 0x4038aa3b, v15
	v_exp_f32_e32 v16, v16
	s_nop 0
	v_add_f32_e32 v16, 1.0, v16
	v_rcp_f32_e32 v16, v16
	s_nop 0
	v_fma_f32 v16, v16, -2.0, 1.0
	v_bfi_b32 v7, s73, v14, v7
	v_mul_f32_e32 v8, 0.5, v8
	v_add_f32_e32 v7, 1.0, v7
	v_mul_f32_e32 v7, v8, v7
	v_mul_f32_e32 v8, 0.5, v9
	v_bfi_b32 v9, s73, v16, v15
	s_or_b32 s8, s4, 4
	v_add_f32_e32 v9, 1.0, v9
	v_mul_f32_e32 v8, v8, v9
	s_ashr_i32 s9, s8, 31
	v_cvt_pk_bf16_f32 v7, v7, v8
	v_lshl_add_u64 v[8:9], s[8:9], 0, v[26:27]
	v_lshlrev_b64 v[8:9], 12, v[8:9]
	v_lshl_add_u64 v[8:9], s[6:7], 0, v[8:9]
	v_lshl_add_u64 v[8:9], v[8:9], 0, s[54:55]
	v_mov_b32_e32 v29, v130
	v_lshl_add_u64 v[8:9], v[8:9], 0, v[28:29]
	global_store_dwordx2 v[8:9], v[6:7], off offset:320
	v_mul_f32_e32 v6, 0x3d372713, v18
	v_mul_f32_e32 v6, v18, v6
	v_fma_f32 v6, v18, v6, v18
	v_mul_f32_e32 v6, 0x3f4c422a, v6
	v_mul_f32_e32 v7, 0x4038aa3b, v6
	v_exp_f32_e32 v7, v7
	s_nop 0
	v_add_f32_e32 v7, 1.0, v7
	v_rcp_f32_e32 v7, v7
	s_nop 0
	v_fma_f32 v7, v7, -2.0, 1.0
	v_mul_f32_e32 v8, 0x3d372713, v19
	v_mul_f32_e32 v8, v19, v8
	v_fma_f32 v8, v19, v8, v19
	v_mul_f32_e32 v8, 0x3f4c422a, v8
	v_mul_f32_e32 v9, 0x4038aa3b, v8
	v_exp_f32_e32 v9, v9
	s_nop 0
	v_add_f32_e32 v9, 1.0, v9
	v_rcp_f32_e32 v9, v9
; __device__ __forceinline__ unsigned pk2(float lo, float hi) { unsigned r; asm volatile("v_cvt_pk_bf16_f32 %0, %1, %2" : "=v"(r) : "v"(lo), "v"(hi)); return r; }
; __device__ __forceinline__ float geluf_(float x) { return 0.5f * x * (1.f + tanhf(0.7978845608028654f * (x + 0.044715f * x * x * x))); }
; __device__ __forceinline__ void ph_s5_out(unsigned char* lds_, const bf16_t* Z, const bf16_t* TZB, const bf16_t* CQ, const float2* LP, const float* SLOC, const float* lamT, bf16_t* YG, int nrct, int u0, int ustep) { PH_IDS;
;     ...
; #pragma unroll
;         for (int i = 0; i < 8; ++i) { const int t = wid * 8 + i;
;             fa::u32x2 w; w.x = fa::pk2(geluf_(acc8[i][0]), geluf_(acc8[i][1])); w.y = fa::pk2(geluf_(acc8[i][2]), geluf_(acc8[i][3]));
;             *(fa::u32x2*)(YG + ((size_t)(rcbase + c16) * 64 + t) * ZW + C_S5 + g * 16 + 4 * kq) = w; }
	s_nop 0
	v_fma_f32 v9, v9, -2.0, 1.0
	v_bfi_b32 v6, s73, v7, v6
	v_bfi_b32 v8, s73, v9, v8
	v_mul_f32_e32 v14, 0.5, v18
	v_add_f32_e32 v6, 1.0, v6
	v_mul_f32_e32 v7, 0.5, v19
	v_add_f32_e32 v8, 1.0, v8
	v_mul_f32_e32 v6, v14, v6
	v_mul_f32_e32 v7, v7, v8
	v_cvt_pk_bf16_f32 v6, v6, v7
	v_mul_f32_e32 v7, 0x3d372713, v20
	v_mul_f32_e32 v7, v20, v7
	v_fma_f32 v7, v20, v7, v20
	v_mul_f32_e32 v7, 0x3f4c422a, v7
	v_mul_f32_e32 v8, 0x4038aa3b, v7
	v_exp_f32_e32 v8, v8
	s_nop 0
	v_add_f32_e32 v8, 1.0, v8
	v_rcp_f32_e32 v8, v8
	s_nop 0
	v_fma_f32 v8, v8, -2.0, 1.0
	v_mul_f32_e32 v9, 0x3d372713, v21
	v_mul_f32_e32 v9, v21, v9
	v_fma_f32 v9, v21, v9, v21
	v_mul_f32_e32 v9, 0x3f4c422a, v9
	v_mul_f32_e32 v14, 0x4038aa3b, v9
	v_exp_f32_e32 v14, v14
	s_nop 0
	v_add_f32_e32 v14, 1.0, v14
	v_rcp_f32_e32 v14, v14
	s_nop 0
	v_fma_f32 v14, v14, -2.0, 1.0
	v_bfi_b32 v7, s73, v8, v7
	v_bfi_b32 v9, s73, v14, v9
	v_mul_f32_e32 v15, 0.5, v20
	v_add_f32_e32 v7, 1.0, v7
	s_or_b32 s8, s4, 5
	v_mul_f32_e32 v8, 0.5, v21
	v_add_f32_e32 v9, 1.0, v9
	v_mul_f32_e32 v7, v15, v7
	v_mul_f32_e32 v8, v8, v9
	s_ashr_i32 s9, s8, 31
	v_cvt_pk_bf16_f32 v7, v7, v8
	v_lshl_add_u64 v[8:9], s[8:9], 0, v[26:27]
	v_lshlrev_b64 v[8:9], 12, v[8:9]
	v_lshl_add_u64 v[8:9], s[6:7], 0, v[8:9]
	v_lshl_add_u64 v[8:9], v[8:9], 0, s[54:55]
	v_mov_b32_e32 v29, v130
	v_lshl_add_u64 v[8:9], v[8:9], 0, v[28:29]
	global_store_dwordx2 v[8:9], v[6:7], off offset:320
	v_mul_f32_e32 v6, 0x3d372713, v2
	v_mul_f32_e32 v6, v2, v6
	v_fma_f32 v6, v2, v6, v2
	v_mul_f32_e32 v6, 0x3f4c422a, v6
	v_mul_f32_e32 v7, 0x4038aa3b, v6
	v_exp_f32_e32 v7, v7
	s_nop 0
	v_add_f32_e32 v7, 1.0, v7
	v_rcp_f32_e32 v7, v7
	s_nop 0
	v_fma_f32 v7, v7, -2.0, 1.0
	v_mul_f32_e32 v8, 0x3d372713, v3
	v_mul_f32_e32 v8, v3, v8
	v_fma_f32 v8, v3, v8, v3
	v_mul_f32_e32 v8, 0x3f4c422a, v8
	v_mul_f32_e32 v9, 0x4038aa3b, v8
	v_exp_f32_e32 v9, v9
	s_nop 0
	v_add_f32_e32 v9, 1.0, v9
	v_rcp_f32_e32 v9, v9
	s_nop 0
	v_fma_f32 v9, v9, -2.0, 1.0
	v_bfi_b32 v6, s73, v7, v6
	v_mul_f32_e32 v2, 0.5, v2
	v_add_f32_e32 v6, 1.0, v6
	v_mul_f32_e32 v2, v2, v6
	v_bfi_b32 v6, s73, v9, v8
	v_mul_f32_e32 v3, 0.5, v3
	v_add_f32_e32 v6, 1.0, v6
	v_mul_f32_e32 v3, v3, v6
	v_cvt_pk_bf16_f32 v2, v2, v3
	v_mul_f32_e32 v3, 0x3d372713, v4
	v_mul_f32_e32 v3, v4, v3
	v_fma_f32 v3, v4, v3, v4
	v_mul_f32_e32 v3, 0x3f4c422a, v3
	v_mul_f32_e32 v6, 0x4038aa3b, v3
	v_exp_f32_e32 v6, v6
	s_nop 0
	v_add_f32_e32 v6, 1.0, v6
	v_rcp_f32_e32 v6, v6
	s_nop 0
	v_fma_f32 v6, v6, -2.0, 1.0
	v_mul_f32_e32 v7, 0x3d372713, v5
	v_mul_f32_e32 v7, v5, v7
	v_fma_f32 v7, v5, v7, v5
	v_mul_f32_e32 v7, 0x3f4c422a, v7
	v_mul_f32_e32 v8, 0x4038aa3b, v7
	v_exp_f32_e32 v8, v8
	s_nop 0
	v_add_f32_e32 v8, 1.0, v8
	v_rcp_f32_e32 v8, v8
	s_nop 0
	v_fma_f32 v8, v8, -2.0, 1.0
	v_bfi_b32 v3, s73, v6, v3
	v_mul_f32_e32 v4, 0.5, v4
	v_add_f32_e32 v3, 1.0, v3
	v_mul_f32_e32 v3, v4, v3
	v_mul_f32_e32 v4, 0.5, v5
	v_bfi_b32 v5, s73, v8, v7
	s_or_b32 s8, s4, 6
	v_add_f32_e32 v5, 1.0, v5
	v_mul_f32_e32 v4, v4, v5
	s_ashr_i32 s9, s8, 31
	v_cvt_pk_bf16_f32 v3, v3, v4
	v_lshl_add_u64 v[4:5], s[8:9], 0, v[26:27]
	v_lshlrev_b64 v[4:5], 12, v[4:5]
	v_lshl_add_u64 v[4:5], s[6:7], 0, v[4:5]
	v_lshl_add_u64 v[4:5], v[4:5], 0, s[54:55]
	v_mov_b32_e32 v29, v130
	v_lshl_add_u64 v[4:5], v[4:5], 0, v[28:29]
	global_store_dwordx2 v[4:5], v[2:3], off offset:320
	v_mul_f32_e32 v2, 0x3d372713, v10
	v_mul_f32_e32 v2, v10, v2
	v_fma_f32 v2, v10, v2, v10
	v_mul_f32_e32 v2, 0x3f4c422a, v2
	v_mul_f32_e32 v3, 0x4038aa3b, v2
	v_exp_f32_e32 v3, v3
	s_nop 0
	v_add_f32_e32 v3, 1.0, v3
	v_rcp_f32_e32 v3, v3
	s_nop 0
	v_fma_f32 v3, v3, -2.0, 1.0
	v_mul_f32_e32 v4, 0x3d372713, v11
	v_mul_f32_e32 v4, v11, v4
	v_fma_f32 v4, v11, v4, v11
	v_mul_f32_e32 v4, 0x3f4c422a, v4
	v_mul_f32_e32 v5, 0x4038aa3b, v4
	v_exp_f32_e32 v5, v5
	s_nop 0
	v_add_f32_e32 v5, 1.0, v5
	v_rcp_f32_e32 v5, v5
	s_nop 0
	v_fma_f32 v5, v5, -2.0, 1.0
	v_bfi_b32 v2, s73, v3, v2
	v_bfi_b32 v4, s73, v5, v4
	v_mul_f32_e32 v6, 0.5, v10
	v_add_f32_e32 v2, 1.0, v2
	v_mul_f32_e32 v3, 0.5, v11
	v_add_f32_e32 v4, 1.0, v4
	v_mul_f32_e32 v2, v6, v2
	v_mul_f32_e32 v3, v3, v4
	v_cvt_pk_bf16_f32 v2, v2, v3
	v_mul_f32_e32 v3, 0x3d372713, v12
	v_mul_f32_e32 v3, v12, v3
	v_fma_f32 v3, v12, v3, v12
	v_mul_f32_e32 v3, 0x3f4c422a, v3
	v_mul_f32_e32 v4, 0x4038aa3b, v3
	v_exp_f32_e32 v4, v4
	s_nop 0
	v_add_f32_e32 v4, 1.0, v4
	v_rcp_f32_e32 v4, v4
	s_nop 0
	v_fma_f32 v4, v4, -2.0, 1.0
	v_mul_f32_e32 v5, 0x3d372713, v13
	v_mul_f32_e32 v5, v13, v5
	v_fma_f32 v5, v13, v5, v13
	v_mul_f32_e32 v5, 0x3f4c422a, v5
	v_mul_f32_e32 v6, 0x4038aa3b, v5
	v_exp_f32_e32 v6, v6
	s_nop 0
	v_add_f32_e32 v6, 1.0, v6
	v_rcp_f32_e32 v6, v6
	s_nop 0
	v_fma_f32 v6, v6, -2.0, 1.0
	v_bfi_b32 v3, s73, v4, v3
	v_bfi_b32 v5, s73, v6, v5
	v_mul_f32_e32 v7, 0.5, v12
	v_add_f32_e32 v3, 1.0, v3
	s_or_b32 s4, s4, 7
	v_mul_f32_e32 v4, 0.5, v13
	v_add_f32_e32 v5, 1.0, v5
	v_mul_f32_e32 v3, v7, v3
	v_mul_f32_e32 v4, v4, v5
	s_ashr_i32 s5, s4, 31
	v_cvt_pk_bf16_f32 v3, v3, v4
	v_lshl_add_u64 v[4:5], s[4:5], 0, v[26:27]
	v_lshlrev_b64 v[4:5], 12, v[4:5]
	v_lshl_add_u64 v[4:5], s[6:7], 0, v[4:5]
	v_lshl_add_u64 v[4:5], v[4:5], 0, s[54:55]
	v_mov_b32_e32 v29, v130
	v_lshl_add_u64 v[4:5], v[4:5], 0, v[28:29]
	global_store_dwordx2 v[4:5], v[2:3], off offset:320
	s_barrier
	s_mov_b64 s[6:7], 0
